# hand epilogue for all 4 scale-GEMMs (P1,P6,P8,P16): 6/16 stores deferred, sumsq prefetched in K loop; pre-header waits removed
# speedup vs baseline: 1.0202x; 1.0180x over previous
.LBB0_155:
	s_lshl_b32 s36, s36, 5
	s_and_b32 s44, s36, 0x60
	s_lshl_b32 s7, s5, 13
	s_lshl_b32 s45, s44, 7
	s_add_u32 s36, s10, 0x1fe00000
	s_addc_u32 s37, s11, 0
	s_add_u32 s38, s10, 0x7a00000
	s_mov_b64 s[40:41], 0x80
	s_addc_u32 s39, s11, 0
	s_add_i32 m0, s33, 0x18000
	v_lshl_add_u64 v[6:7], v[6:7], 0, s[40:41]
	s_waitcnt vmcnt(4)
	s_barrier
	global_load_lds_dwordx4 v[6:7], off
	v_lshl_add_u64 v[4:5], v[4:5], 0, s[40:41]
	s_add_i32 m0, s33, 0x1a000
	s_add_i32 s56, s33, 0x8000
	s_add_i32 s57, s33, 0xa000
	global_load_lds_dwordx4 v[4:5], off
	v_lshl_add_u64 v[2:3], v[2:3], 0, s[40:41]
	s_mov_b32 m0, s56
	s_add_u32 s42, s52, 0x40080
	global_load_lds_dwordx4 v[2:3], off
	v_lshl_add_u64 v[0:1], v[0:1], 0, s[40:41]
	s_mov_b32 m0, s57
	s_addc_u32 s43, s53, 0
	global_load_lds_dwordx4 v[0:1], off
	s_add_i32 m0, s33, 0x1c000
	v_lshl_add_u64 v[0:1], s[42:43], 0, v[132:133]
	global_load_lds_dwordx4 v[0:1], off
	v_lshl_add_u64 v[0:1], s[42:43], 0, v[128:129]
	s_add_i32 m0, s33, 0x1e000
	s_add_i32 s60, 0, 0x10000
	global_load_lds_dwordx4 v[0:1], off
	v_lshrrev_b32_e32 v1, 1, v9
	v_and_b32_e32 v1, 24, v1
	v_and_b32_e32 v0, 15, v9
	v_lshlrev_b32_e32 v2, 1, v1
	v_lshl_or_b32 v153, s5, 6, v0
	v_lshl_or_b32 v0, v0, 6, v2
	v_lshlrev_b32_e32 v2, 2, v9
	v_and_b32_e32 v2, 32, v2
	v_bitop3_b32 v3, v0, s7, v2 bitop3:0xde
	v_bitop3_b32 v154, v0, s45, v2 bitop3:0xde
	v_lshlrev_b32_e32 v0, 14, v13
	v_and_b32_e32 v0, 0xffff8000, v0
	v_or_b32_e32 v155, s44, v1
	v_lshl_add_u32 v0, v12, 11, v0
	v_and_b32_e32 v1, 1, v13
	v_lshl_or_b32 v0, v1, 6, v0
	v_lshl_add_u32 v136, v14, 1, v0
	v_lshlrev_b32_e32 v0, 14, v8
	v_and_b32_e32 v0, 0xffff8000, v0
	s_waitcnt vmcnt(6)
	v_lshl_add_u32 v0, v10, 11, v0
	v_and_b32_e32 v1, 1, v8
	v_lshl_or_b32 v0, v1, 6, v0
	s_add_i32 s61, 0, 0x14000
	s_sext_i32_i8 s64, s4
	s_ashr_i32 s58, s22, 31
	s_mov_b32 s59, s22
	v_mov_b32_e32 v137, v133
	v_lshl_add_u32 v138, v11, 1, v0
	v_mov_b32_e32 v139, v133
	v_mov_b64_e32 v[140:141], 0x700
	v_mov_b64_e32 v[142:143], 0x6ff
	v_add_u32_e32 v156, s60, v154
	v_add_u32_e32 v157, 0, v3
	v_add_u32_e32 v158, s61, v154
	v_mov_b32_e32 v159, 0x358637bd
	s_mov_b32 s62, 0x800000
	s_movk_i32 s63, 0x1c00
	s_barrier
	s_mov_b32 s32, 0
	v_mul_u32_u24_e32 v239, 0x1c00, v153
	v_lshl_add_u32 v239, v155, 1, v239

.LBB0_159:
	ds_read_b128 v[144:147], v156
	ds_read_b128 v[148:151], v156 offset:1024
	ds_read_b128 v[160:163], v156 offset:2048
	ds_read_b128 v[164:167], v156 offset:3072
	s_add_u32 s52, s8, 0xfffc0080
	s_addc_u32 s53, s9, -1
	s_cmp_eq_u32 s68, 12
	s_cselect_b32 s55, s7, s53
	s_cselect_b32 s54, s45, s52
	s_cselect_b32 s53, s43, s67
	s_cselect_b32 s52, s65, s66
	v_lshl_add_u64 v[200:201], s[8:9], 0, v[136:137]
	s_add_i32 m0, s33, 0xc000
	ds_read_b128 v[168:171], v157
	ds_read_b128 v[172:175], v157 offset:1024
	ds_read_b128 v[176:179], v157 offset:2048
	ds_read_b128 v[180:183], v157 offset:3072
	ds_read_b128 v[184:187], v157 offset:4096
	ds_read_b128 v[188:191], v157 offset:5120
	ds_read_b128 v[192:195], v157 offset:6144
	ds_read_b128 v[196:199], v157 offset:7168
	global_load_lds_dwordx4 v[200:201], off
	v_lshl_add_u64 v[200:201], s[8:9], 0, v[138:139]
	s_add_i32 m0, s33, 0xe000
	s_nop 0
	global_load_lds_dwordx4 v[200:201], off
	s_waitcnt lgkmcnt(8)
	s_barrier
	s_waitcnt lgkmcnt(0)
	s_setprio 1
	s_waitcnt lgkmcnt(0)
	v_mfma_f32_16x16x32_bf16 v[124:127], v[144:147], v[168:171], v[124:127]
	v_mfma_f32_16x16x32_bf16 v[120:123], v[160:163], v[168:171], v[120:123]
	v_mfma_f32_16x16x32_bf16 v[116:119], v[144:147], v[176:179], v[116:119]
	v_mfma_f32_16x16x32_bf16 v[108:111], v[160:163], v[176:179], v[108:111]
	v_mfma_f32_16x16x32_bf16 v[100:103], v[144:147], v[184:187], v[100:103]
	v_mfma_f32_16x16x32_bf16 v[92:95], v[160:163], v[184:187], v[92:95]
	v_mfma_f32_16x16x32_bf16 v[84:87], v[144:147], v[192:195], v[84:87]
	v_mfma_f32_16x16x32_bf16 v[76:79], v[160:163], v[192:195], v[76:79]
	v_mfma_f32_16x16x32_bf16 v[124:127], v[148:151], v[172:175], v[124:127]
	v_mfma_f32_16x16x32_bf16 v[120:123], v[164:167], v[172:175], v[120:123]
	v_mfma_f32_16x16x32_bf16 v[116:119], v[148:151], v[180:183], v[116:119]
	v_mfma_f32_16x16x32_bf16 v[108:111], v[164:167], v[180:183], v[108:111]
	v_mfma_f32_16x16x32_bf16 v[100:103], v[148:151], v[188:191], v[100:103]
	v_mfma_f32_16x16x32_bf16 v[92:95], v[164:167], v[188:191], v[92:95]
	v_mfma_f32_16x16x32_bf16 v[84:87], v[148:151], v[196:199], v[84:87]
	v_mfma_f32_16x16x32_bf16 v[76:79], v[164:167], v[196:199], v[76:79]
	s_setprio 0
	s_barrier
	s_add_i32 s69, s60, s1
	v_lshl_add_u64 v[218:219], s[52:53], 0, v[132:133]
	s_mov_b32 m0, s69
	ds_read_b128 v[200:203], v158
	ds_read_b128 v[206:209], v158 offset:1024
	ds_read_b128 v[210:213], v158 offset:2048
	ds_read_b128 v[214:217], v158 offset:3072
	global_load_lds_dwordx4 v[218:219], off
	v_lshl_add_u64 v[220:221], s[52:53], 0, v[128:129]
	s_add_i32 m0, s69, 0x2000
	s_nop 0
	global_load_lds_dwordx4 v[220:221], off
	s_barrier
	s_waitcnt lgkmcnt(0)
	s_setprio 1
	s_waitcnt lgkmcnt(0)
	v_mfma_f32_16x16x32_bf16 v[112:115], v[200:203], v[168:171], v[112:115]
	v_mfma_f32_16x16x32_bf16 v[104:107], v[210:213], v[168:171], v[104:107]
	v_mfma_f32_16x16x32_bf16 v[96:99], v[200:203], v[176:179], v[96:99]
	v_mfma_f32_16x16x32_bf16 v[88:91], v[210:213], v[176:179], v[88:91]
	v_mfma_f32_16x16x32_bf16 v[80:83], v[200:203], v[184:187], v[80:83]
	v_mfma_f32_16x16x32_bf16 v[72:75], v[210:213], v[184:187], v[72:75]
	v_mfma_f32_16x16x32_bf16 v[68:71], v[200:203], v[192:195], v[68:71]
	v_mfma_f32_16x16x32_bf16 v[64:67], v[210:213], v[192:195], v[64:67]
	v_mfma_f32_16x16x32_bf16 v[112:115], v[206:209], v[172:175], v[112:115]
	v_mfma_f32_16x16x32_bf16 v[104:107], v[214:217], v[172:175], v[104:107]
	v_mfma_f32_16x16x32_bf16 v[96:99], v[206:209], v[180:183], v[96:99]
	v_mfma_f32_16x16x32_bf16 v[88:91], v[214:217], v[180:183], v[88:91]
	v_mfma_f32_16x16x32_bf16 v[80:83], v[206:209], v[188:191], v[80:83]
	v_mfma_f32_16x16x32_bf16 v[72:75], v[214:217], v[188:191], v[72:75]
	v_mfma_f32_16x16x32_bf16 v[68:71], v[206:209], v[196:199], v[68:71]
	v_mfma_f32_16x16x32_bf16 v[64:67], v[214:217], v[196:199], v[64:67]
	s_setprio 0
	s_mov_b32 m0, s33
	v_lshl_add_u64 v[222:223], s[54:55], 0, v[134:135]
	s_barrier
	ds_read_b128 v[168:171], v157 offset:16384
	ds_read_b128 v[172:175], v157 offset:17408
	ds_read_b128 v[176:179], v157 offset:18432
	ds_read_b128 v[180:183], v157 offset:19456
	ds_read_b128 v[184:187], v157 offset:20480
	ds_read_b128 v[188:191], v157 offset:21504
	ds_read_b128 v[192:195], v157 offset:22528
	ds_read_b128 v[196:199], v157 offset:23552
	global_load_lds_dwordx4 v[222:223], off
	v_lshl_add_u64 v[224:225], s[54:55], 0, v[130:131]
	s_mov_b32 m0, s34
	s_nop 0
	global_load_lds_dwordx4 v[224:225], off
	s_barrier
	s_waitcnt lgkmcnt(0)
	s_setprio 1
	s_waitcnt lgkmcnt(0)
	v_mfma_f32_16x16x32_bf16 v[60:63], v[144:147], v[168:171], v[60:63]
	v_mfma_f32_16x16x32_bf16 v[56:59], v[160:163], v[168:171], v[56:59]
	v_mfma_f32_16x16x32_bf16 v[52:55], v[144:147], v[176:179], v[52:55]
	v_mfma_f32_16x16x32_bf16 v[44:47], v[160:163], v[176:179], v[44:47]
	v_mfma_f32_16x16x32_bf16 v[36:39], v[144:147], v[184:187], v[36:39]
	v_mfma_f32_16x16x32_bf16 v[28:31], v[160:163], v[184:187], v[28:31]
	v_mfma_f32_16x16x32_bf16 v[20:23], v[144:147], v[192:195], v[20:23]
	v_mfma_f32_16x16x32_bf16 v[12:15], v[160:163], v[192:195], v[12:15]
	v_mfma_f32_16x16x32_bf16 v[60:63], v[148:151], v[172:175], v[60:63]
	v_mfma_f32_16x16x32_bf16 v[56:59], v[164:167], v[172:175], v[56:59]
	v_mfma_f32_16x16x32_bf16 v[52:55], v[148:151], v[180:183], v[52:55]
	v_mfma_f32_16x16x32_bf16 v[44:47], v[164:167], v[180:183], v[44:47]
	v_mfma_f32_16x16x32_bf16 v[36:39], v[148:151], v[188:191], v[36:39]
	v_mfma_f32_16x16x32_bf16 v[28:31], v[164:167], v[188:191], v[28:31]
	v_mfma_f32_16x16x32_bf16 v[20:23], v[148:151], v[196:199], v[20:23]
	v_mfma_f32_16x16x32_bf16 v[12:15], v[164:167], v[196:199], v[12:15]
	s_setprio 0
	s_barrier
	s_add_u32 s70, s52, 0x40000
	s_addc_u32 s71, s53, 0
	s_add_i32 s69, s61, s1
	v_lshl_add_u64 v[144:145], s[70:71], 0, v[132:133]
	s_mov_b32 m0, s69
	s_nop 0
	global_load_lds_dwordx4 v[144:145], off
	v_lshl_add_u64 v[144:145], s[70:71], 0, v[128:129]
	s_add_i32 m0, s69, 0x2000
	s_nop 0
	global_load_lds_dwordx4 v[144:145], off
	s_waitcnt vmcnt(6)
	s_cmp_gt_u32 s68, 6
	s_cbranch_scc1 .Lds_P1_a_done
	s_cmp_eq_u32 s68, 6
	s_cbranch_scc1 .Lds_P1_a_pf
	s_cmp_eq_u32 s32, 0
	s_cbranch_scc1 .Lds_P1_a_done
	s_cmp_eq_u32 s68, 0
	s_cbranch_scc1 .Lds_P1_a_0
	s_cmp_eq_u32 s68, 2
	s_cbranch_scc1 .Lds_P1_a_1
	s_add_u32 s100, s98, 0x134000
	s_addc_u32 s101, s99, 0
	global_store_dwordx4 v239, v[248:251], s[100:101]
	s_branch .Lds_P1_a_done
.Lds_P1_a_1:
	s_add_u32 s100, s98, 0x118000
	s_addc_u32 s101, s99, 0
	global_store_dwordx4 v239, v[240:243], s[100:101]
	s_branch .Lds_P1_a_done
.Lds_P1_a_0:
	s_add_u32 s100, s98, 0xfc000
	s_addc_u32 s101, s99, 0
	global_store_dwordx4 v239, v[230:233], s[100:101]
	s_branch .Lds_P1_a_done
.Lds_P1_a_pf:
	s_lshl_b32 s82, s6, 11
	s_add_u32 s100, s36, s82
	s_addc_u32 s101, s37, 0
	v_lshlrev_b32_e32 v252, 3, v153
	global_load_dwordx2 v[230:231], v252, s[100:101]
	global_load_dwordx2 v[232:233], v252, s[100:101] offset:128
	global_load_dwordx2 v[234:235], v252, s[100:101] offset:256
	global_load_dwordx2 v[236:237], v252, s[100:101] offset:384
	global_load_dwordx2 v[240:241], v252, s[100:101] offset:1024
	global_load_dwordx2 v[242:243], v252, s[100:101] offset:1152
	global_load_dwordx2 v[244:245], v252, s[100:101] offset:1280
	global_load_dwordx2 v[246:247], v252, s[100:101] offset:1408
.Lds_P1_a_done:
	s_barrier
	s_setprio 1
	v_mfma_f32_16x16x32_bf16 v[48:51], v[200:203], v[168:171], v[48:51]
	v_mfma_f32_16x16x32_bf16 v[40:43], v[210:213], v[168:171], v[40:43]
	v_mfma_f32_16x16x32_bf16 v[32:35], v[200:203], v[176:179], v[32:35]
	v_mfma_f32_16x16x32_bf16 v[24:27], v[210:213], v[176:179], v[24:27]
	v_mfma_f32_16x16x32_bf16 v[16:19], v[200:203], v[184:187], v[16:19]
	v_mfma_f32_16x16x32_bf16 v[8:11], v[210:213], v[184:187], v[8:11]
	v_mfma_f32_16x16x32_bf16 v[4:7], v[200:203], v[192:195], v[4:7]
	v_mfma_f32_16x16x32_bf16 v[0:3], v[210:213], v[192:195], v[0:3]
	v_mfma_f32_16x16x32_bf16 v[48:51], v[206:209], v[172:175], v[48:51]
	v_mfma_f32_16x16x32_bf16 v[40:43], v[214:217], v[172:175], v[40:43]
	v_mfma_f32_16x16x32_bf16 v[32:35], v[206:209], v[180:183], v[32:35]
	v_mfma_f32_16x16x32_bf16 v[24:27], v[214:217], v[180:183], v[24:27]
	v_mfma_f32_16x16x32_bf16 v[16:19], v[206:209], v[188:191], v[16:19]
	v_mfma_f32_16x16x32_bf16 v[8:11], v[214:217], v[188:191], v[8:11]
	v_mfma_f32_16x16x32_bf16 v[4:7], v[206:209], v[196:199], v[4:7]
	v_mfma_f32_16x16x32_bf16 v[0:3], v[214:217], v[196:199], v[0:3]
	s_setprio 0
	s_add_i32 s69, 0, 0x18000
	v_add_u32_e32 v164, s69, v154
	s_barrier
	ds_read_b128 v[144:147], v164
	ds_read_b128 v[148:151], v164 offset:1024
	ds_read_b128 v[160:163], v164 offset:2048
	ds_read_b128 v[164:167], v164 offset:3072
	s_add_u32 s54, s54, 0x40000
	s_addc_u32 s55, s55, 0
	s_mov_b32 m0, s35
	v_lshl_add_u64 v[200:201], s[54:55], 0, v[134:135]
	ds_read_b128 v[168:171], v157 offset:32768
	ds_read_b128 v[172:175], v157 offset:33792
	ds_read_b128 v[176:179], v157 offset:34816
	ds_read_b128 v[180:183], v157 offset:35840
	ds_read_b128 v[184:187], v157 offset:36864
	ds_read_b128 v[188:191], v157 offset:37888
	ds_read_b128 v[192:195], v157 offset:38912
	ds_read_b128 v[196:199], v157 offset:39936
	global_load_lds_dwordx4 v[200:201], off
	v_lshl_add_u64 v[200:201], s[54:55], 0, v[130:131]
	s_mov_b32 m0, s46
	s_nop 0
	global_load_lds_dwordx4 v[200:201], off
	s_waitcnt lgkmcnt(8)
	s_barrier
	s_waitcnt lgkmcnt(0)
	s_setprio 1
	s_waitcnt lgkmcnt(0)
	v_mfma_f32_16x16x32_bf16 v[124:127], v[144:147], v[168:171], v[124:127]
	v_mfma_f32_16x16x32_bf16 v[120:123], v[160:163], v[168:171], v[120:123]
	v_mfma_f32_16x16x32_bf16 v[116:119], v[144:147], v[176:179], v[116:119]
	v_mfma_f32_16x16x32_bf16 v[108:111], v[160:163], v[176:179], v[108:111]
	v_mfma_f32_16x16x32_bf16 v[100:103], v[144:147], v[184:187], v[100:103]
	v_mfma_f32_16x16x32_bf16 v[92:95], v[160:163], v[184:187], v[92:95]
	v_mfma_f32_16x16x32_bf16 v[84:87], v[144:147], v[192:195], v[84:87]
	v_mfma_f32_16x16x32_bf16 v[76:79], v[160:163], v[192:195], v[76:79]
	v_mfma_f32_16x16x32_bf16 v[124:127], v[148:151], v[172:175], v[124:127]
	v_mfma_f32_16x16x32_bf16 v[120:123], v[164:167], v[172:175], v[120:123]
	v_mfma_f32_16x16x32_bf16 v[116:119], v[148:151], v[180:183], v[116:119]
	v_mfma_f32_16x16x32_bf16 v[108:111], v[164:167], v[180:183], v[108:111]
	v_mfma_f32_16x16x32_bf16 v[100:103], v[148:151], v[188:191], v[100:103]
	v_mfma_f32_16x16x32_bf16 v[92:95], v[164:167], v[188:191], v[92:95]
	v_mfma_f32_16x16x32_bf16 v[84:87], v[148:151], v[196:199], v[84:87]
	v_mfma_f32_16x16x32_bf16 v[76:79], v[164:167], v[196:199], v[76:79]
	s_setprio 0
	s_barrier
	s_add_i32 s54, 0, 0x1c000
	s_add_i32 s55, s69, s1
	v_add_u32_e32 v205, s54, v154
	v_lshl_add_u64 v[218:219], v[218:219], 0, s[40:41]
	s_mov_b32 m0, s55
	ds_read_b128 v[200:203], v205
	ds_read_b128 v[206:209], v205 offset:1024
	ds_read_b128 v[210:213], v205 offset:2048
	ds_read_b128 v[214:217], v205 offset:3072
	global_load_lds_dwordx4 v[218:219], off
	v_lshl_add_u64 v[218:219], v[220:221], 0, s[40:41]
	s_add_i32 m0, s55, 0x2000
	s_nop 0
	global_load_lds_dwordx4 v[218:219], off
	s_barrier
	s_waitcnt lgkmcnt(0)
	s_setprio 1
	s_waitcnt lgkmcnt(0)
	v_mfma_f32_16x16x32_bf16 v[112:115], v[200:203], v[168:171], v[112:115]
	v_mfma_f32_16x16x32_bf16 v[104:107], v[210:213], v[168:171], v[104:107]
	v_mfma_f32_16x16x32_bf16 v[96:99], v[200:203], v[176:179], v[96:99]
	v_mfma_f32_16x16x32_bf16 v[88:91], v[210:213], v[176:179], v[88:91]
	v_mfma_f32_16x16x32_bf16 v[80:83], v[200:203], v[184:187], v[80:83]
	v_mfma_f32_16x16x32_bf16 v[72:75], v[210:213], v[184:187], v[72:75]
	v_mfma_f32_16x16x32_bf16 v[68:71], v[200:203], v[192:195], v[68:71]
	v_mfma_f32_16x16x32_bf16 v[64:67], v[210:213], v[192:195], v[64:67]
	v_mfma_f32_16x16x32_bf16 v[112:115], v[206:209], v[172:175], v[112:115]
	v_mfma_f32_16x16x32_bf16 v[104:107], v[214:217], v[172:175], v[104:107]
	v_mfma_f32_16x16x32_bf16 v[96:99], v[206:209], v[180:183], v[96:99]
	v_mfma_f32_16x16x32_bf16 v[88:91], v[214:217], v[180:183], v[88:91]
	v_mfma_f32_16x16x32_bf16 v[80:83], v[206:209], v[188:191], v[80:83]
	v_mfma_f32_16x16x32_bf16 v[72:75], v[214:217], v[188:191], v[72:75]
	v_mfma_f32_16x16x32_bf16 v[68:71], v[206:209], v[196:199], v[68:71]
	v_mfma_f32_16x16x32_bf16 v[64:67], v[214:217], v[196:199], v[64:67]
	s_setprio 0
	s_mov_b32 m0, s56
	v_lshl_add_u64 v[218:219], v[222:223], 0, s[40:41]
	s_barrier
	ds_read_b128 v[168:171], v157 offset:49152
	ds_read_b128 v[172:175], v157 offset:50176
	ds_read_b128 v[176:179], v157 offset:51200
	ds_read_b128 v[180:183], v157 offset:52224
	ds_read_b128 v[184:187], v157 offset:53248
	ds_read_b128 v[188:191], v157 offset:54272
	ds_read_b128 v[192:195], v157 offset:55296
	ds_read_b128 v[196:199], v157 offset:56320
	global_load_lds_dwordx4 v[218:219], off
	v_lshl_add_u64 v[218:219], v[224:225], 0, s[40:41]
	s_mov_b32 m0, s57
	s_nop 0
	global_load_lds_dwordx4 v[218:219], off
	s_barrier
	s_waitcnt lgkmcnt(0)
	s_setprio 1
	s_waitcnt lgkmcnt(0)
	v_mfma_f32_16x16x32_bf16 v[60:63], v[144:147], v[168:171], v[60:63]
	v_mfma_f32_16x16x32_bf16 v[56:59], v[160:163], v[168:171], v[56:59]
	v_mfma_f32_16x16x32_bf16 v[52:55], v[144:147], v[176:179], v[52:55]
	v_mfma_f32_16x16x32_bf16 v[44:47], v[160:163], v[176:179], v[44:47]
	v_mfma_f32_16x16x32_bf16 v[36:39], v[144:147], v[184:187], v[36:39]
	v_mfma_f32_16x16x32_bf16 v[28:31], v[160:163], v[184:187], v[28:31]
	v_mfma_f32_16x16x32_bf16 v[20:23], v[144:147], v[192:195], v[20:23]
	v_mfma_f32_16x16x32_bf16 v[12:15], v[160:163], v[192:195], v[12:15]
	v_mfma_f32_16x16x32_bf16 v[60:63], v[148:151], v[172:175], v[60:63]
	v_mfma_f32_16x16x32_bf16 v[56:59], v[164:167], v[172:175], v[56:59]
	v_mfma_f32_16x16x32_bf16 v[52:55], v[148:151], v[180:183], v[52:55]
	v_mfma_f32_16x16x32_bf16 v[44:47], v[164:167], v[180:183], v[44:47]
	v_mfma_f32_16x16x32_bf16 v[36:39], v[148:151], v[188:191], v[36:39]
	v_mfma_f32_16x16x32_bf16 v[28:31], v[164:167], v[188:191], v[28:31]
	v_mfma_f32_16x16x32_bf16 v[20:23], v[148:151], v[196:199], v[20:23]
	v_mfma_f32_16x16x32_bf16 v[12:15], v[164:167], v[196:199], v[12:15]
	s_setprio 0
	s_barrier
	s_add_u32 s52, s52, 0x40080
	s_addc_u32 s53, s53, 0
	s_add_i32 s54, s54, s1
	v_lshl_add_u64 v[144:145], s[52:53], 0, v[132:133]
	s_mov_b32 m0, s54
	s_nop 0
	global_load_lds_dwordx4 v[144:145], off
	v_lshl_add_u64 v[144:145], s[52:53], 0, v[128:129]
	s_add_i32 m0, s54, 0x2000
	s_nop 0
	global_load_lds_dwordx4 v[144:145], off
	s_waitcnt vmcnt(6)
	s_cmp_gt_u32 s68, 4
	s_cbranch_scc1 .Lds_P1_b_done
	s_cmp_eq_u32 s32, 0
	s_cbranch_scc1 .Lds_P1_b_done
	s_cmp_eq_u32 s68, 0
	s_cbranch_scc1 .Lds_P1_b_0
	s_cmp_eq_u32 s68, 2
	s_cbranch_scc1 .Lds_P1_b_1
	s_add_u32 s100, s98, 0x134000
	s_addc_u32 s101, s99, 0
	global_store_dwordx4 v239, v[252:255], s[100:101] offset:256
	s_branch .Lds_P1_b_done
.Lds_P1_b_1:
	s_add_u32 s100, s98, 0x118000
	s_addc_u32 s101, s99, 0
	global_store_dwordx4 v239, v[244:247], s[100:101] offset:256
	s_branch .Lds_P1_b_done
.Lds_P1_b_0:
	s_add_u32 s100, s98, 0xfc000
	s_addc_u32 s101, s99, 0
	global_store_dwordx4 v239, v[234:237], s[100:101] offset:256
.Lds_P1_b_done:
	s_barrier
	s_setprio 1
	v_mfma_f32_16x16x32_bf16 v[48:51], v[200:203], v[168:171], v[48:51]
	v_mfma_f32_16x16x32_bf16 v[40:43], v[210:213], v[168:171], v[40:43]
	v_mfma_f32_16x16x32_bf16 v[32:35], v[200:203], v[176:179], v[32:35]
	v_mfma_f32_16x16x32_bf16 v[24:27], v[210:213], v[176:179], v[24:27]
	v_mfma_f32_16x16x32_bf16 v[16:19], v[200:203], v[184:187], v[16:19]
	v_mfma_f32_16x16x32_bf16 v[8:11], v[210:213], v[184:187], v[8:11]
	v_mfma_f32_16x16x32_bf16 v[4:7], v[200:203], v[192:195], v[4:7]
	v_mfma_f32_16x16x32_bf16 v[0:3], v[210:213], v[192:195], v[0:3]
	v_mfma_f32_16x16x32_bf16 v[48:51], v[206:209], v[172:175], v[48:51]
	v_mfma_f32_16x16x32_bf16 v[40:43], v[214:217], v[172:175], v[40:43]
	v_mfma_f32_16x16x32_bf16 v[32:35], v[206:209], v[180:183], v[32:35]
	v_mfma_f32_16x16x32_bf16 v[24:27], v[214:217], v[180:183], v[24:27]
	v_mfma_f32_16x16x32_bf16 v[16:19], v[206:209], v[188:191], v[16:19]
	v_mfma_f32_16x16x32_bf16 v[8:11], v[214:217], v[188:191], v[8:11]
	v_mfma_f32_16x16x32_bf16 v[4:7], v[206:209], v[196:199], v[4:7]
	v_mfma_f32_16x16x32_bf16 v[0:3], v[214:217], v[196:199], v[0:3]
	s_setprio 0
	s_add_i32 s68, s68, 2
	s_add_u32 s8, s8, 0x100
	s_addc_u32 s9, s9, 0
	s_add_u32 s66, s66, 0x100
	s_addc_u32 s67, s67, 0
	s_cmp_gt_u32 s68, 13
	s_barrier
	s_cbranch_scc0 .LBB0_159
.Lepi_P1_start:
	s_mul_i32 s82, s6, 0x1c0000
	s_lshl_b32 s84, s64, 9
	s_add_u32 s82, s82, s84
	s_add_u32 s84, s38, s82
	s_addc_u32 s85, s39, 0
	v_mov_b32_e32 v168, 0x358637bd
	v_ffbh_u32_e32 v160, v231
	v_ffbh_u32_e32 v161, v233
	v_ffbh_u32_e32 v162, v235
	v_ffbh_u32_e32 v163, v237
	v_ffbh_u32_e32 v164, v241
	v_ffbh_u32_e32 v165, v243
	v_ffbh_u32_e32 v166, v245
	v_ffbh_u32_e32 v167, v247
	v_min_u32_e32 v160, 32, v160
	v_min_u32_e32 v161, 32, v161
	v_min_u32_e32 v162, 32, v162
	v_min_u32_e32 v163, 32, v163
	v_min_u32_e32 v164, 32, v164
	v_min_u32_e32 v165, 32, v165
	v_min_u32_e32 v166, 32, v166
	v_min_u32_e32 v167, 32, v167
	v_lshlrev_b64 v[230:231], v160, v[230:231]
	v_lshlrev_b64 v[232:233], v161, v[232:233]
	v_lshlrev_b64 v[234:235], v162, v[234:235]
	v_lshlrev_b64 v[236:237], v163, v[236:237]
	v_lshlrev_b64 v[240:241], v164, v[240:241]
	v_lshlrev_b64 v[242:243], v165, v[242:243]
	v_lshlrev_b64 v[244:245], v166, v[244:245]
	v_lshlrev_b64 v[246:247], v167, v[246:247]
	v_min_u32_e32 v230, 1, v230
	v_min_u32_e32 v232, 1, v232
	v_min_u32_e32 v234, 1, v234
	v_min_u32_e32 v236, 1, v236
	v_min_u32_e32 v240, 1, v240
	v_min_u32_e32 v242, 1, v242
	v_min_u32_e32 v244, 1, v244
	v_min_u32_e32 v246, 1, v246
	v_or_b32_e32 v231, v231, v230
	v_or_b32_e32 v233, v233, v232
	v_or_b32_e32 v235, v235, v234
	v_or_b32_e32 v237, v237, v236
	v_or_b32_e32 v241, v241, v240
	v_or_b32_e32 v243, v243, v242
	v_or_b32_e32 v245, v245, v244
	v_or_b32_e32 v247, v247, v246
	v_cvt_f32_u32_e32 v231, v231
	v_cvt_f32_u32_e32 v233, v233
	v_cvt_f32_u32_e32 v235, v235
	v_cvt_f32_u32_e32 v237, v237
	v_cvt_f32_u32_e32 v241, v241
	v_cvt_f32_u32_e32 v243, v243
	v_cvt_f32_u32_e32 v245, v245
	v_cvt_f32_u32_e32 v247, v247
	v_sub_u32_e32 v160, 32, v160
	v_sub_u32_e32 v161, 32, v161
	v_sub_u32_e32 v162, 32, v162
	v_sub_u32_e32 v163, 32, v163
	v_sub_u32_e32 v164, 32, v164
	v_sub_u32_e32 v165, 32, v165
	v_sub_u32_e32 v166, 32, v166
	v_sub_u32_e32 v167, 32, v167
	v_ldexp_f32 v231, v231, v160
	v_ldexp_f32 v233, v233, v161
	v_ldexp_f32 v235, v235, v162
	v_ldexp_f32 v237, v237, v163
	v_ldexp_f32 v241, v241, v164
	v_ldexp_f32 v243, v243, v165
	v_ldexp_f32 v245, v245, v166
	v_ldexp_f32 v247, v247, v167
	v_fmamk_f32 v231, v231, 0x2e800000, v168
	v_fmamk_f32 v233, v233, 0x2e800000, v168
	v_fmamk_f32 v235, v235, 0x2e800000, v168
	v_fmamk_f32 v237, v237, 0x2e800000, v168
	v_fmamk_f32 v241, v241, 0x2e800000, v168
	v_fmamk_f32 v243, v243, 0x2e800000, v168
	v_fmamk_f32 v245, v245, 0x2e800000, v168
	v_fmamk_f32 v247, v247, 0x2e800000, v168
	v_rsq_f32_e32 v144, v231
	v_rsq_f32_e32 v145, v233
	v_rsq_f32_e32 v146, v235
	v_rsq_f32_e32 v147, v237
	v_rsq_f32_e32 v148, v241
	v_rsq_f32_e32 v149, v243
	v_rsq_f32_e32 v150, v245
	v_rsq_f32_e32 v151, v247
	s_nop 0
	v_pk_mul_f32 v[124:125], v[124:125], v[144:145] op_sel_hi:[1,0]
	v_pk_mul_f32 v[126:127], v[126:127], v[144:145] op_sel_hi:[1,0]
	v_pk_mul_f32 v[120:121], v[120:121], v[144:145] op_sel_hi:[1,0]
	v_pk_mul_f32 v[122:123], v[122:123], v[144:145] op_sel_hi:[1,0]
	v_cvt_pk_bf16_f32 v124, v124, v125
	v_cvt_pk_bf16_f32 v125, v126, v127
	v_cvt_pk_bf16_f32 v126, v120, v121
	v_cvt_pk_bf16_f32 v127, v122, v123
	global_store_dwordx4 v239, v[124:127], s[84:85]
	v_pk_mul_f32 v[112:113], v[112:113], v[144:145] op_sel_hi:[1,0]
	v_pk_mul_f32 v[114:115], v[114:115], v[144:145] op_sel_hi:[1,0]
	v_pk_mul_f32 v[104:105], v[104:105], v[144:145] op_sel_hi:[1,0]
	v_pk_mul_f32 v[106:107], v[106:107], v[144:145] op_sel_hi:[1,0]
	v_cvt_pk_bf16_f32 v112, v112, v113
	v_cvt_pk_bf16_f32 v113, v114, v115
	v_cvt_pk_bf16_f32 v114, v104, v105
	v_cvt_pk_bf16_f32 v115, v106, v107
	global_store_dwordx4 v239, v[112:115], s[84:85] offset:256
	v_pk_mul_f32 v[116:117], v[116:117], v[144:145] op_sel:[0,1] op_sel_hi:[1,1]
	v_pk_mul_f32 v[118:119], v[118:119], v[144:145] op_sel:[0,1] op_sel_hi:[1,1]
	v_pk_mul_f32 v[108:109], v[108:109], v[144:145] op_sel:[0,1] op_sel_hi:[1,1]
	v_pk_mul_f32 v[110:111], v[110:111], v[144:145] op_sel:[0,1] op_sel_hi:[1,1]
	v_cvt_pk_bf16_f32 v116, v116, v117
	v_cvt_pk_bf16_f32 v117, v118, v119
	v_cvt_pk_bf16_f32 v118, v108, v109
	v_cvt_pk_bf16_f32 v119, v110, v111
	s_add_u32 s100, s84, 0x1c000
	s_addc_u32 s101, s85, 0
	global_store_dwordx4 v239, v[116:119], s[100:101]
	v_pk_mul_f32 v[96:97], v[96:97], v[144:145] op_sel:[0,1] op_sel_hi:[1,1]
	v_pk_mul_f32 v[98:99], v[98:99], v[144:145] op_sel:[0,1] op_sel_hi:[1,1]
	v_pk_mul_f32 v[88:89], v[88:89], v[144:145] op_sel:[0,1] op_sel_hi:[1,1]
	v_pk_mul_f32 v[90:91], v[90:91], v[144:145] op_sel:[0,1] op_sel_hi:[1,1]
	v_cvt_pk_bf16_f32 v96, v96, v97
	v_cvt_pk_bf16_f32 v97, v98, v99
	v_cvt_pk_bf16_f32 v98, v88, v89
	v_cvt_pk_bf16_f32 v99, v90, v91
	s_add_u32 s100, s84, 0x1c000
	s_addc_u32 s101, s85, 0
	global_store_dwordx4 v239, v[96:99], s[100:101] offset:256
	v_pk_mul_f32 v[100:101], v[100:101], v[146:147] op_sel_hi:[1,0]
	v_pk_mul_f32 v[102:103], v[102:103], v[146:147] op_sel_hi:[1,0]
	v_pk_mul_f32 v[92:93], v[92:93], v[146:147] op_sel_hi:[1,0]
	v_pk_mul_f32 v[94:95], v[94:95], v[146:147] op_sel_hi:[1,0]
	v_cvt_pk_bf16_f32 v100, v100, v101
	v_cvt_pk_bf16_f32 v101, v102, v103
	v_cvt_pk_bf16_f32 v102, v92, v93
	v_cvt_pk_bf16_f32 v103, v94, v95
	s_add_u32 s100, s84, 0x38000
	s_addc_u32 s101, s85, 0
	global_store_dwordx4 v239, v[100:103], s[100:101]
	v_pk_mul_f32 v[80:81], v[80:81], v[146:147] op_sel_hi:[1,0]
	v_pk_mul_f32 v[82:83], v[82:83], v[146:147] op_sel_hi:[1,0]
	v_pk_mul_f32 v[72:73], v[72:73], v[146:147] op_sel_hi:[1,0]
	v_pk_mul_f32 v[74:75], v[74:75], v[146:147] op_sel_hi:[1,0]
	v_cvt_pk_bf16_f32 v80, v80, v81
	v_cvt_pk_bf16_f32 v81, v82, v83
	v_cvt_pk_bf16_f32 v82, v72, v73
	v_cvt_pk_bf16_f32 v83, v74, v75
	s_add_u32 s100, s84, 0x38000
	s_addc_u32 s101, s85, 0
	global_store_dwordx4 v239, v[80:83], s[100:101] offset:256
	v_pk_mul_f32 v[84:85], v[84:85], v[146:147] op_sel:[0,1] op_sel_hi:[1,1]
	v_pk_mul_f32 v[86:87], v[86:87], v[146:147] op_sel:[0,1] op_sel_hi:[1,1]
	v_pk_mul_f32 v[76:77], v[76:77], v[146:147] op_sel:[0,1] op_sel_hi:[1,1]
	v_pk_mul_f32 v[78:79], v[78:79], v[146:147] op_sel:[0,1] op_sel_hi:[1,1]
	v_cvt_pk_bf16_f32 v84, v84, v85
	v_cvt_pk_bf16_f32 v85, v86, v87
	v_cvt_pk_bf16_f32 v86, v76, v77
	v_cvt_pk_bf16_f32 v87, v78, v79
	s_add_u32 s100, s84, 0x54000
	s_addc_u32 s101, s85, 0
	global_store_dwordx4 v239, v[84:87], s[100:101]
	v_pk_mul_f32 v[68:69], v[68:69], v[146:147] op_sel:[0,1] op_sel_hi:[1,1]
	v_pk_mul_f32 v[70:71], v[70:71], v[146:147] op_sel:[0,1] op_sel_hi:[1,1]
	v_pk_mul_f32 v[64:65], v[64:65], v[146:147] op_sel:[0,1] op_sel_hi:[1,1]
	v_pk_mul_f32 v[66:67], v[66:67], v[146:147] op_sel:[0,1] op_sel_hi:[1,1]
	v_cvt_pk_bf16_f32 v68, v68, v69
	v_cvt_pk_bf16_f32 v69, v70, v71
	v_cvt_pk_bf16_f32 v70, v64, v65
	v_cvt_pk_bf16_f32 v71, v66, v67
	s_add_u32 s100, s84, 0x54000
	s_addc_u32 s101, s85, 0
	global_store_dwordx4 v239, v[68:71], s[100:101] offset:256
	v_pk_mul_f32 v[60:61], v[60:61], v[148:149] op_sel_hi:[1,0]
	v_pk_mul_f32 v[62:63], v[62:63], v[148:149] op_sel_hi:[1,0]
	v_pk_mul_f32 v[56:57], v[56:57], v[148:149] op_sel_hi:[1,0]
	v_pk_mul_f32 v[58:59], v[58:59], v[148:149] op_sel_hi:[1,0]
	v_cvt_pk_bf16_f32 v60, v60, v61
	v_cvt_pk_bf16_f32 v61, v62, v63
	v_cvt_pk_bf16_f32 v62, v56, v57
	v_cvt_pk_bf16_f32 v63, v58, v59
	s_add_u32 s100, s84, 0xe0000
	s_addc_u32 s101, s85, 0
	global_store_dwordx4 v239, v[60:63], s[100:101]
	v_pk_mul_f32 v[48:49], v[48:49], v[148:149] op_sel_hi:[1,0]
	v_pk_mul_f32 v[50:51], v[50:51], v[148:149] op_sel_hi:[1,0]
	v_pk_mul_f32 v[40:41], v[40:41], v[148:149] op_sel_hi:[1,0]
	v_pk_mul_f32 v[42:43], v[42:43], v[148:149] op_sel_hi:[1,0]
	v_cvt_pk_bf16_f32 v48, v48, v49
	v_cvt_pk_bf16_f32 v49, v50, v51
	v_cvt_pk_bf16_f32 v50, v40, v41
	v_cvt_pk_bf16_f32 v51, v42, v43
	s_add_u32 s100, s84, 0xe0000
	s_addc_u32 s101, s85, 0
	global_store_dwordx4 v239, v[48:51], s[100:101] offset:256
	v_pk_mul_f32 v[52:53], v[52:53], v[148:149] op_sel:[0,1] op_sel_hi:[1,1]
	v_pk_mul_f32 v[54:55], v[54:55], v[148:149] op_sel:[0,1] op_sel_hi:[1,1]
	v_pk_mul_f32 v[44:45], v[44:45], v[148:149] op_sel:[0,1] op_sel_hi:[1,1]
	v_pk_mul_f32 v[46:47], v[46:47], v[148:149] op_sel:[0,1] op_sel_hi:[1,1]
	v_cvt_pk_bf16_f32 v230, v52, v53
	v_cvt_pk_bf16_f32 v231, v54, v55
	v_cvt_pk_bf16_f32 v232, v44, v45
	v_cvt_pk_bf16_f32 v233, v46, v47
	v_pk_mul_f32 v[32:33], v[32:33], v[148:149] op_sel:[0,1] op_sel_hi:[1,1]
	v_pk_mul_f32 v[34:35], v[34:35], v[148:149] op_sel:[0,1] op_sel_hi:[1,1]
	v_pk_mul_f32 v[24:25], v[24:25], v[148:149] op_sel:[0,1] op_sel_hi:[1,1]
	v_pk_mul_f32 v[26:27], v[26:27], v[148:149] op_sel:[0,1] op_sel_hi:[1,1]
	v_cvt_pk_bf16_f32 v234, v32, v33
	v_cvt_pk_bf16_f32 v235, v34, v35
	v_cvt_pk_bf16_f32 v236, v24, v25
	v_cvt_pk_bf16_f32 v237, v26, v27
	v_pk_mul_f32 v[36:37], v[36:37], v[150:151] op_sel_hi:[1,0]
	v_pk_mul_f32 v[38:39], v[38:39], v[150:151] op_sel_hi:[1,0]
	v_pk_mul_f32 v[28:29], v[28:29], v[150:151] op_sel_hi:[1,0]
	v_pk_mul_f32 v[30:31], v[30:31], v[150:151] op_sel_hi:[1,0]
	v_cvt_pk_bf16_f32 v240, v36, v37
	v_cvt_pk_bf16_f32 v241, v38, v39
	v_cvt_pk_bf16_f32 v242, v28, v29
	v_cvt_pk_bf16_f32 v243, v30, v31
	v_pk_mul_f32 v[16:17], v[16:17], v[150:151] op_sel_hi:[1,0]
	v_pk_mul_f32 v[18:19], v[18:19], v[150:151] op_sel_hi:[1,0]
	v_pk_mul_f32 v[8:9], v[8:9], v[150:151] op_sel_hi:[1,0]
	v_pk_mul_f32 v[10:11], v[10:11], v[150:151] op_sel_hi:[1,0]
	v_cvt_pk_bf16_f32 v244, v16, v17
	v_cvt_pk_bf16_f32 v245, v18, v19
	v_cvt_pk_bf16_f32 v246, v8, v9
	v_cvt_pk_bf16_f32 v247, v10, v11
	v_pk_mul_f32 v[20:21], v[20:21], v[150:151] op_sel:[0,1] op_sel_hi:[1,1]
	v_pk_mul_f32 v[22:23], v[22:23], v[150:151] op_sel:[0,1] op_sel_hi:[1,1]
	v_pk_mul_f32 v[12:13], v[12:13], v[150:151] op_sel:[0,1] op_sel_hi:[1,1]
	v_pk_mul_f32 v[14:15], v[14:15], v[150:151] op_sel:[0,1] op_sel_hi:[1,1]
	v_cvt_pk_bf16_f32 v248, v20, v21
	v_cvt_pk_bf16_f32 v249, v22, v23
	v_cvt_pk_bf16_f32 v250, v12, v13
	v_cvt_pk_bf16_f32 v251, v14, v15
	v_pk_mul_f32 v[4:5], v[4:5], v[150:151] op_sel:[0,1] op_sel_hi:[1,1]
	v_pk_mul_f32 v[6:7], v[6:7], v[150:151] op_sel:[0,1] op_sel_hi:[1,1]
	v_pk_mul_f32 v[0:1], v[0:1], v[150:151] op_sel:[0,1] op_sel_hi:[1,1]
	v_pk_mul_f32 v[2:3], v[2:3], v[150:151] op_sel:[0,1] op_sel_hi:[1,1]
	v_cvt_pk_bf16_f32 v252, v4, v5
	v_cvt_pk_bf16_f32 v253, v6, v7
	v_cvt_pk_bf16_f32 v254, v0, v1
	v_cvt_pk_bf16_f32 v255, v2, v3
	s_mov_b64 s[52:53], s[50:51]
	s_and_b64 vcc, exec, s[4:5]
	s_mov_b32 s64, s42
	s_mov_b32 s6, s44
	s_mov_b64 s[8:9], s[48:49]
	s_mov_b64 s[98:99], s[84:85]
	s_mov_b32 s32, 1
	s_cbranch_vccz .LBB0_156
	s_add_u32 s100, s84, 0xfc000
	s_addc_u32 s101, s85, 0
	global_store_dwordx4 v239, v[230:233], s[100:101]
	s_add_u32 s100, s84, 0xfc000
	s_addc_u32 s101, s85, 0
	global_store_dwordx4 v239, v[234:237], s[100:101] offset:256
	s_add_u32 s100, s84, 0x118000
	s_addc_u32 s101, s85, 0
	global_store_dwordx4 v239, v[240:243], s[100:101]
	s_add_u32 s100, s84, 0x118000
	s_addc_u32 s101, s85, 0
	global_store_dwordx4 v239, v[244:247], s[100:101] offset:256
	s_add_u32 s100, s84, 0x134000
	s_addc_u32 s101, s85, 0
	global_store_dwordx4 v239, v[248:251], s[100:101]
	s_add_u32 s100, s84, 0x134000
	s_addc_u32 s101, s85, 0
	global_store_dwordx4 v239, v[252:255], s[100:101] offset:256
	s_waitcnt vmcnt(0)
	s_cmpk_gt_u32 s0, 0xff
	s_cbranch_scc1 .LBB0_163
	s_barrier

.LBB0_987:
	ds_read_b128 v[164:167], v155
	ds_read_b128 v[168:171], v155 offset:1024
	ds_read_b128 v[172:175], v155 offset:2048
	ds_read_b128 v[176:179], v155 offset:3072
	s_add_u32 s56, s12, 0xfffc0080
	s_addc_u32 s57, s13, -1
	s_cmp_eq_u32 s71, 12
	s_cselect_b32 s59, s11, s57
	s_cselect_b32 s58, s51, s56
	s_cselect_b32 s57, s39, s70
	s_cselect_b32 s56, s68, s69
	v_lshl_add_u64 v[146:147], s[12:13], 0, v[136:137]
	s_add_i32 m0, s35, 0xc000
	ds_read_b128 v[180:183], v159
	ds_read_b128 v[184:187], v159 offset:1024
	ds_read_b128 v[188:191], v159 offset:2048
	ds_read_b128 v[192:195], v159 offset:3072
	ds_read_b128 v[196:199], v159 offset:4096
	ds_read_b128 v[200:203], v159 offset:5120
	ds_read_b128 v[206:209], v159 offset:6144
	ds_read_b128 v[210:213], v159 offset:7168
	global_load_lds_dwordx4 v[146:147], off
	v_lshl_add_u64 v[146:147], s[12:13], 0, v[138:139]
	s_add_i32 m0, s35, 0xe000
	s_nop 0
	global_load_lds_dwordx4 v[146:147], off
	s_waitcnt lgkmcnt(8)
	s_barrier
	s_waitcnt lgkmcnt(0)
	s_setprio 1
	s_waitcnt lgkmcnt(0)
	v_mfma_f32_16x16x32_bf16 v[124:127], v[164:167], v[180:183], v[124:127]
	v_mfma_f32_16x16x32_bf16 v[120:123], v[172:175], v[180:183], v[120:123]
	v_mfma_f32_16x16x32_bf16 v[108:111], v[164:167], v[188:191], v[108:111]
	v_mfma_f32_16x16x32_bf16 v[104:107], v[172:175], v[188:191], v[104:107]
	v_mfma_f32_16x16x32_bf16 v[92:95], v[164:167], v[196:199], v[92:95]
	v_mfma_f32_16x16x32_bf16 v[88:91], v[172:175], v[196:199], v[88:91]
	v_mfma_f32_16x16x32_bf16 v[76:79], v[164:167], v[206:209], v[76:79]
	v_mfma_f32_16x16x32_bf16 v[72:75], v[172:175], v[206:209], v[72:75]
	v_mfma_f32_16x16x32_bf16 v[124:127], v[168:171], v[184:187], v[124:127]
	v_mfma_f32_16x16x32_bf16 v[120:123], v[176:179], v[184:187], v[120:123]
	v_mfma_f32_16x16x32_bf16 v[108:111], v[168:171], v[192:195], v[108:111]
	v_mfma_f32_16x16x32_bf16 v[104:107], v[176:179], v[192:195], v[104:107]
	v_mfma_f32_16x16x32_bf16 v[92:95], v[168:171], v[200:203], v[92:95]
	v_mfma_f32_16x16x32_bf16 v[88:91], v[176:179], v[200:203], v[88:91]
	v_mfma_f32_16x16x32_bf16 v[76:79], v[168:171], v[210:213], v[76:79]
	v_mfma_f32_16x16x32_bf16 v[72:75], v[176:179], v[210:213], v[72:75]
	s_setprio 0
	s_barrier
	s_add_i32 s72, s60, s34
	v_lshl_add_u64 v[146:147], s[56:57], 0, v[130:131]
	s_mov_b32 m0, s72
	ds_read_b128 v[214:217], v162
	ds_read_b128 v[218:221], v162 offset:1024
	ds_read_b128 v[222:225], v162 offset:2048
	ds_read_b128 v[226:229], v162 offset:3072
	global_load_lds_dwordx4 v[146:147], off
	v_lshl_add_u64 v[152:153], s[56:57], 0, v[134:135]
	s_add_i32 m0, s72, 0x2000
	s_nop 0
	global_load_lds_dwordx4 v[152:153], off
	s_barrier
	s_waitcnt lgkmcnt(0)
	s_setprio 1
	s_waitcnt lgkmcnt(0)
	v_mfma_f32_16x16x32_bf16 v[116:119], v[214:217], v[180:183], v[116:119]
	v_mfma_f32_16x16x32_bf16 v[112:115], v[222:225], v[180:183], v[112:115]
	v_mfma_f32_16x16x32_bf16 v[100:103], v[214:217], v[188:191], v[100:103]
	v_mfma_f32_16x16x32_bf16 v[96:99], v[222:225], v[188:191], v[96:99]
	v_mfma_f32_16x16x32_bf16 v[84:87], v[214:217], v[196:199], v[84:87]
	v_mfma_f32_16x16x32_bf16 v[80:83], v[222:225], v[196:199], v[80:83]
	v_mfma_f32_16x16x32_bf16 v[68:71], v[214:217], v[206:209], v[68:71]
	v_mfma_f32_16x16x32_bf16 v[64:67], v[222:225], v[206:209], v[64:67]
	v_mfma_f32_16x16x32_bf16 v[116:119], v[218:221], v[184:187], v[116:119]
	v_mfma_f32_16x16x32_bf16 v[112:115], v[226:229], v[184:187], v[112:115]
	v_mfma_f32_16x16x32_bf16 v[100:103], v[218:221], v[192:195], v[100:103]
	v_mfma_f32_16x16x32_bf16 v[96:99], v[226:229], v[192:195], v[96:99]
	v_mfma_f32_16x16x32_bf16 v[84:87], v[218:221], v[200:203], v[84:87]
	v_mfma_f32_16x16x32_bf16 v[80:83], v[226:229], v[200:203], v[80:83]
	v_mfma_f32_16x16x32_bf16 v[68:71], v[218:221], v[210:213], v[68:71]
	v_mfma_f32_16x16x32_bf16 v[64:67], v[226:229], v[210:213], v[64:67]
	s_setprio 0
	s_mov_b32 m0, s35
	v_lshl_add_u64 v[156:157], s[58:59], 0, v[128:129]
	s_barrier
	ds_read_b128 v[180:183], v159 offset:16384
	ds_read_b128 v[184:187], v159 offset:17408
	ds_read_b128 v[188:191], v159 offset:18432
	ds_read_b128 v[192:195], v159 offset:19456
	ds_read_b128 v[196:199], v159 offset:20480
	ds_read_b128 v[200:203], v159 offset:21504
	ds_read_b128 v[206:209], v159 offset:22528
	ds_read_b128 v[210:213], v159 offset:23552
	global_load_lds_dwordx4 v[156:157], off
	v_lshl_add_u64 v[160:161], s[58:59], 0, v[132:133]
	s_mov_b32 m0, s42
	s_nop 0
	global_load_lds_dwordx4 v[160:161], off
	s_barrier
	s_waitcnt lgkmcnt(0)
	s_setprio 1
	s_waitcnt lgkmcnt(0)
	v_mfma_f32_16x16x32_bf16 v[60:63], v[164:167], v[180:183], v[60:63]
	v_mfma_f32_16x16x32_bf16 v[56:59], v[172:175], v[180:183], v[56:59]
	v_mfma_f32_16x16x32_bf16 v[44:47], v[164:167], v[188:191], v[44:47]
	v_mfma_f32_16x16x32_bf16 v[40:43], v[172:175], v[188:191], v[40:43]
	v_mfma_f32_16x16x32_bf16 v[28:31], v[164:167], v[196:199], v[28:31]
	v_mfma_f32_16x16x32_bf16 v[24:27], v[172:175], v[196:199], v[24:27]
	v_mfma_f32_16x16x32_bf16 v[12:15], v[164:167], v[206:209], v[12:15]
	v_mfma_f32_16x16x32_bf16 v[8:11], v[172:175], v[206:209], v[8:11]
	v_mfma_f32_16x16x32_bf16 v[60:63], v[168:171], v[184:187], v[60:63]
	v_mfma_f32_16x16x32_bf16 v[56:59], v[176:179], v[184:187], v[56:59]
	v_mfma_f32_16x16x32_bf16 v[44:47], v[168:171], v[192:195], v[44:47]
	v_mfma_f32_16x16x32_bf16 v[40:43], v[176:179], v[192:195], v[40:43]
	v_mfma_f32_16x16x32_bf16 v[28:31], v[168:171], v[200:203], v[28:31]
	v_mfma_f32_16x16x32_bf16 v[24:27], v[176:179], v[200:203], v[24:27]
	v_mfma_f32_16x16x32_bf16 v[12:15], v[168:171], v[210:213], v[12:15]
	v_mfma_f32_16x16x32_bf16 v[8:11], v[176:179], v[210:213], v[8:11]
	s_setprio 0
	s_barrier
	s_add_u32 s72, s56, 0x40000
	s_addc_u32 s73, s57, 0
	s_add_i32 s74, s61, s34
	v_lshl_add_u64 v[164:165], s[72:73], 0, v[130:131]
	s_mov_b32 m0, s74
	s_nop 0
	global_load_lds_dwordx4 v[164:165], off
	v_lshl_add_u64 v[164:165], s[72:73], 0, v[134:135]
	s_add_i32 m0, s74, 0x2000
	s_nop 0
	global_load_lds_dwordx4 v[164:165], off
	s_waitcnt vmcnt(6)
	s_cmp_gt_u32 s71, 6
	s_cbranch_scc1 .Lds_P6_a_done
	s_cmp_eq_u32 s71, 6
	s_cbranch_scc1 .Lds_P6_a_pf
	s_cmp_eq_u32 s32, 0
	s_cbranch_scc1 .Lds_P6_a_done
	s_cmp_eq_u32 s71, 0
	s_cbranch_scc1 .Lds_P6_a_0
	s_cmp_eq_u32 s71, 2
	s_cbranch_scc1 .Lds_P6_a_1
	s_add_u32 s100, s98, 0x160000
	s_addc_u32 s101, s99, 0
	global_store_dwordx4 v239, v[248:251], s[100:101]
	s_branch .Lds_P6_a_done

.Lds_P6_a_0:
	s_add_u32 s100, s98, 0x120000
	s_addc_u32 s101, s99, 0
	global_store_dwordx4 v239, v[230:233], s[100:101]
	s_branch .Lds_P6_a_done
.Lds_P6_a_pf:
	s_lshl_b32 s82, s10, 11
	s_add_u32 s100, s18, s82
	s_addc_u32 s101, s19, 0
	v_lshlrev_b32_e32 v252, 3, v145
	global_load_dwordx2 v[230:231], v252, s[100:101]
	global_load_dwordx2 v[232:233], v252, s[100:101] offset:128
	global_load_dwordx2 v[234:235], v252, s[100:101] offset:256
	global_load_dwordx2 v[236:237], v252, s[100:101] offset:384
	global_load_dwordx2 v[240:241], v252, s[100:101] offset:1024
	global_load_dwordx2 v[242:243], v252, s[100:101] offset:1152
	global_load_dwordx2 v[244:245], v252, s[100:101] offset:1280
	global_load_dwordx2 v[246:247], v252, s[100:101] offset:1408

.Lepi_P6_start:
	s_mul_i32 s82, s10, 0x200000
	s_lshl_b32 s84, s67, 9
	s_add_u32 s82, s82, s84
	s_add_u32 s84, s16, s82
	s_addc_u32 s85, s17, 0
	v_mov_b32_e32 v144, 0x358637bd
	v_ffbh_u32_e32 v172, v231
	v_ffbh_u32_e32 v173, v233
	v_ffbh_u32_e32 v174, v235
	v_ffbh_u32_e32 v175, v237
	v_ffbh_u32_e32 v176, v241
	v_ffbh_u32_e32 v177, v243
	v_ffbh_u32_e32 v178, v245
	v_ffbh_u32_e32 v179, v247
	v_min_u32_e32 v172, 32, v172
	v_min_u32_e32 v173, 32, v173
	v_min_u32_e32 v174, 32, v174
	v_min_u32_e32 v175, 32, v175
	v_min_u32_e32 v176, 32, v176
	v_min_u32_e32 v177, 32, v177
	v_min_u32_e32 v178, 32, v178
	v_min_u32_e32 v179, 32, v179
	v_lshlrev_b64 v[230:231], v172, v[230:231]
	v_lshlrev_b64 v[232:233], v173, v[232:233]
	v_lshlrev_b64 v[234:235], v174, v[234:235]
	v_lshlrev_b64 v[236:237], v175, v[236:237]
	v_lshlrev_b64 v[240:241], v176, v[240:241]
	v_lshlrev_b64 v[242:243], v177, v[242:243]
	v_lshlrev_b64 v[244:245], v178, v[244:245]
	v_lshlrev_b64 v[246:247], v179, v[246:247]
	v_min_u32_e32 v230, 1, v230
	v_min_u32_e32 v232, 1, v232
	v_min_u32_e32 v234, 1, v234
	v_min_u32_e32 v236, 1, v236
	v_min_u32_e32 v240, 1, v240
	v_min_u32_e32 v242, 1, v242
	v_min_u32_e32 v244, 1, v244
	v_min_u32_e32 v246, 1, v246
	v_or_b32_e32 v231, v231, v230
	v_or_b32_e32 v233, v233, v232
	v_or_b32_e32 v235, v235, v234
	v_or_b32_e32 v237, v237, v236
	v_or_b32_e32 v241, v241, v240
	v_or_b32_e32 v243, v243, v242
	v_or_b32_e32 v245, v245, v244
	v_or_b32_e32 v247, v247, v246
	v_cvt_f32_u32_e32 v231, v231
	v_cvt_f32_u32_e32 v233, v233
	v_cvt_f32_u32_e32 v235, v235
	v_cvt_f32_u32_e32 v237, v237
	v_cvt_f32_u32_e32 v241, v241
	v_cvt_f32_u32_e32 v243, v243
	v_cvt_f32_u32_e32 v245, v245
	v_cvt_f32_u32_e32 v247, v247
	v_sub_u32_e32 v172, 32, v172
	v_sub_u32_e32 v173, 32, v173
	v_sub_u32_e32 v174, 32, v174
	v_sub_u32_e32 v175, 32, v175
	v_sub_u32_e32 v176, 32, v176
	v_sub_u32_e32 v177, 32, v177
	v_sub_u32_e32 v178, 32, v178
	v_sub_u32_e32 v179, 32, v179
	v_ldexp_f32 v231, v231, v172
	v_ldexp_f32 v233, v233, v173
	v_ldexp_f32 v235, v235, v174
	v_ldexp_f32 v237, v237, v175
	v_ldexp_f32 v241, v241, v176
	v_ldexp_f32 v243, v243, v177
	v_ldexp_f32 v245, v245, v178
	v_ldexp_f32 v247, v247, v179
	v_fmamk_f32 v231, v231, 0x2e800000, v144
	v_fmamk_f32 v233, v233, 0x2e800000, v144
	v_fmamk_f32 v235, v235, 0x2e800000, v144
	v_fmamk_f32 v237, v237, 0x2e800000, v144
	v_fmamk_f32 v241, v241, 0x2e800000, v144
	v_fmamk_f32 v243, v243, 0x2e800000, v144
	v_fmamk_f32 v245, v245, 0x2e800000, v144
	v_fmamk_f32 v247, v247, 0x2e800000, v144
	v_rsq_f32_e32 v164, v231
	v_rsq_f32_e32 v165, v233
	v_rsq_f32_e32 v166, v235
	v_rsq_f32_e32 v167, v237
	v_rsq_f32_e32 v168, v241
	v_rsq_f32_e32 v169, v243
	v_rsq_f32_e32 v170, v245
	v_rsq_f32_e32 v171, v247
	s_nop 0
	v_pk_mul_f32 v[124:125], v[124:125], v[164:165] op_sel_hi:[1,0]
	v_pk_mul_f32 v[126:127], v[126:127], v[164:165] op_sel_hi:[1,0]
	v_pk_mul_f32 v[120:121], v[120:121], v[164:165] op_sel_hi:[1,0]
	v_pk_mul_f32 v[122:123], v[122:123], v[164:165] op_sel_hi:[1,0]
	v_max_f32_e32 v124, 0, v124
	v_max_f32_e32 v125, 0, v125
	v_max_f32_e32 v126, 0, v126
	v_max_f32_e32 v127, 0, v127
	v_max_f32_e32 v120, 0, v120
	v_max_f32_e32 v121, 0, v121
	v_max_f32_e32 v122, 0, v122
	v_max_f32_e32 v123, 0, v123
	v_pk_mul_f32 v[124:125], v[124:125], v[124:125]
	v_pk_mul_f32 v[126:127], v[126:127], v[126:127]
	v_pk_mul_f32 v[120:121], v[120:121], v[120:121]
	v_pk_mul_f32 v[122:123], v[122:123], v[122:123]
	v_cvt_pk_bf16_f32 v124, v124, v125
	v_cvt_pk_bf16_f32 v125, v126, v127
	v_cvt_pk_bf16_f32 v126, v120, v121
	v_cvt_pk_bf16_f32 v127, v122, v123
	global_store_dwordx4 v239, v[124:127], s[84:85]
	v_pk_mul_f32 v[116:117], v[116:117], v[164:165] op_sel_hi:[1,0]
	v_pk_mul_f32 v[118:119], v[118:119], v[164:165] op_sel_hi:[1,0]
	v_pk_mul_f32 v[112:113], v[112:113], v[164:165] op_sel_hi:[1,0]
	v_pk_mul_f32 v[114:115], v[114:115], v[164:165] op_sel_hi:[1,0]
	v_max_f32_e32 v116, 0, v116
	v_max_f32_e32 v117, 0, v117
	v_max_f32_e32 v118, 0, v118
	v_max_f32_e32 v119, 0, v119
	v_max_f32_e32 v112, 0, v112
	v_max_f32_e32 v113, 0, v113
	v_max_f32_e32 v114, 0, v114
	v_max_f32_e32 v115, 0, v115
	v_pk_mul_f32 v[116:117], v[116:117], v[116:117]
	v_pk_mul_f32 v[118:119], v[118:119], v[118:119]
	v_pk_mul_f32 v[112:113], v[112:113], v[112:113]
	v_pk_mul_f32 v[114:115], v[114:115], v[114:115]
	v_cvt_pk_bf16_f32 v116, v116, v117
	v_cvt_pk_bf16_f32 v117, v118, v119
	v_cvt_pk_bf16_f32 v118, v112, v113
	v_cvt_pk_bf16_f32 v119, v114, v115
	global_store_dwordx4 v239, v[116:119], s[84:85] offset:256
	v_pk_mul_f32 v[108:109], v[108:109], v[164:165] op_sel:[0,1] op_sel_hi:[1,1]
	v_pk_mul_f32 v[110:111], v[110:111], v[164:165] op_sel:[0,1] op_sel_hi:[1,1]
	v_pk_mul_f32 v[104:105], v[104:105], v[164:165] op_sel:[0,1] op_sel_hi:[1,1]
	v_pk_mul_f32 v[106:107], v[106:107], v[164:165] op_sel:[0,1] op_sel_hi:[1,1]
	v_max_f32_e32 v108, 0, v108
	v_max_f32_e32 v109, 0, v109
	v_max_f32_e32 v110, 0, v110
	v_max_f32_e32 v111, 0, v111
	v_max_f32_e32 v104, 0, v104
	v_max_f32_e32 v105, 0, v105
	v_max_f32_e32 v106, 0, v106
	v_max_f32_e32 v107, 0, v107
	v_pk_mul_f32 v[108:109], v[108:109], v[108:109]
	v_pk_mul_f32 v[110:111], v[110:111], v[110:111]
	v_pk_mul_f32 v[104:105], v[104:105], v[104:105]
	v_pk_mul_f32 v[106:107], v[106:107], v[106:107]
	v_cvt_pk_bf16_f32 v108, v108, v109
	v_cvt_pk_bf16_f32 v109, v110, v111
	v_cvt_pk_bf16_f32 v110, v104, v105
	v_cvt_pk_bf16_f32 v111, v106, v107
	s_add_u32 s100, s84, 0x20000
	s_addc_u32 s101, s85, 0
	global_store_dwordx4 v239, v[108:111], s[100:101]
	v_pk_mul_f32 v[100:101], v[100:101], v[164:165] op_sel:[0,1] op_sel_hi:[1,1]
	v_pk_mul_f32 v[102:103], v[102:103], v[164:165] op_sel:[0,1] op_sel_hi:[1,1]
	v_pk_mul_f32 v[96:97], v[96:97], v[164:165] op_sel:[0,1] op_sel_hi:[1,1]
	v_pk_mul_f32 v[98:99], v[98:99], v[164:165] op_sel:[0,1] op_sel_hi:[1,1]
	v_max_f32_e32 v100, 0, v100
	v_max_f32_e32 v101, 0, v101
	v_max_f32_e32 v102, 0, v102
	v_max_f32_e32 v103, 0, v103
	v_max_f32_e32 v96, 0, v96
	v_max_f32_e32 v97, 0, v97
	v_max_f32_e32 v98, 0, v98
	v_max_f32_e32 v99, 0, v99
	v_pk_mul_f32 v[100:101], v[100:101], v[100:101]
	v_pk_mul_f32 v[102:103], v[102:103], v[102:103]
	v_pk_mul_f32 v[96:97], v[96:97], v[96:97]
	v_pk_mul_f32 v[98:99], v[98:99], v[98:99]
	v_cvt_pk_bf16_f32 v100, v100, v101
	v_cvt_pk_bf16_f32 v101, v102, v103
	v_cvt_pk_bf16_f32 v102, v96, v97
	v_cvt_pk_bf16_f32 v103, v98, v99
	s_add_u32 s100, s84, 0x20000
	s_addc_u32 s101, s85, 0
	global_store_dwordx4 v239, v[100:103], s[100:101] offset:256
	v_pk_mul_f32 v[92:93], v[92:93], v[166:167] op_sel_hi:[1,0]
	v_pk_mul_f32 v[94:95], v[94:95], v[166:167] op_sel_hi:[1,0]
	v_pk_mul_f32 v[88:89], v[88:89], v[166:167] op_sel_hi:[1,0]
	v_pk_mul_f32 v[90:91], v[90:91], v[166:167] op_sel_hi:[1,0]
	v_max_f32_e32 v92, 0, v92
	v_max_f32_e32 v93, 0, v93
	v_max_f32_e32 v94, 0, v94
	v_max_f32_e32 v95, 0, v95
	v_max_f32_e32 v88, 0, v88
	v_max_f32_e32 v89, 0, v89
	v_max_f32_e32 v90, 0, v90
	v_max_f32_e32 v91, 0, v91
	v_pk_mul_f32 v[92:93], v[92:93], v[92:93]
	v_pk_mul_f32 v[94:95], v[94:95], v[94:95]
	v_pk_mul_f32 v[88:89], v[88:89], v[88:89]
	v_pk_mul_f32 v[90:91], v[90:91], v[90:91]
	v_cvt_pk_bf16_f32 v92, v92, v93
	v_cvt_pk_bf16_f32 v93, v94, v95
	v_cvt_pk_bf16_f32 v94, v88, v89
	v_cvt_pk_bf16_f32 v95, v90, v91
	s_add_u32 s100, s84, 0x40000
	s_addc_u32 s101, s85, 0
	global_store_dwordx4 v239, v[92:95], s[100:101]
	v_pk_mul_f32 v[84:85], v[84:85], v[166:167] op_sel_hi:[1,0]
	v_pk_mul_f32 v[86:87], v[86:87], v[166:167] op_sel_hi:[1,0]
	v_pk_mul_f32 v[80:81], v[80:81], v[166:167] op_sel_hi:[1,0]
	v_pk_mul_f32 v[82:83], v[82:83], v[166:167] op_sel_hi:[1,0]
	v_max_f32_e32 v84, 0, v84
	v_max_f32_e32 v85, 0, v85
	v_max_f32_e32 v86, 0, v86
	v_max_f32_e32 v87, 0, v87
	v_max_f32_e32 v80, 0, v80
	v_max_f32_e32 v81, 0, v81
	v_max_f32_e32 v82, 0, v82
	v_max_f32_e32 v83, 0, v83
	v_pk_mul_f32 v[84:85], v[84:85], v[84:85]
	v_pk_mul_f32 v[86:87], v[86:87], v[86:87]
	v_pk_mul_f32 v[80:81], v[80:81], v[80:81]
	v_pk_mul_f32 v[82:83], v[82:83], v[82:83]
	v_cvt_pk_bf16_f32 v84, v84, v85
	v_cvt_pk_bf16_f32 v85, v86, v87
	v_cvt_pk_bf16_f32 v86, v80, v81
	v_cvt_pk_bf16_f32 v87, v82, v83
	s_add_u32 s100, s84, 0x40000
	s_addc_u32 s101, s85, 0
	global_store_dwordx4 v239, v[84:87], s[100:101] offset:256
	v_pk_mul_f32 v[76:77], v[76:77], v[166:167] op_sel:[0,1] op_sel_hi:[1,1]
	v_pk_mul_f32 v[78:79], v[78:79], v[166:167] op_sel:[0,1] op_sel_hi:[1,1]
	v_pk_mul_f32 v[72:73], v[72:73], v[166:167] op_sel:[0,1] op_sel_hi:[1,1]
	v_pk_mul_f32 v[74:75], v[74:75], v[166:167] op_sel:[0,1] op_sel_hi:[1,1]
	v_max_f32_e32 v76, 0, v76
	v_max_f32_e32 v77, 0, v77
	v_max_f32_e32 v78, 0, v78
	v_max_f32_e32 v79, 0, v79
	v_max_f32_e32 v72, 0, v72
	v_max_f32_e32 v73, 0, v73
	v_max_f32_e32 v74, 0, v74
	v_max_f32_e32 v75, 0, v75
	v_pk_mul_f32 v[76:77], v[76:77], v[76:77]
	v_pk_mul_f32 v[78:79], v[78:79], v[78:79]
	v_pk_mul_f32 v[72:73], v[72:73], v[72:73]
	v_pk_mul_f32 v[74:75], v[74:75], v[74:75]
	v_cvt_pk_bf16_f32 v76, v76, v77
	v_cvt_pk_bf16_f32 v77, v78, v79
	v_cvt_pk_bf16_f32 v78, v72, v73
	v_cvt_pk_bf16_f32 v79, v74, v75
	s_add_u32 s100, s84, 0x60000
	s_addc_u32 s101, s85, 0
	global_store_dwordx4 v239, v[76:79], s[100:101]
	v_pk_mul_f32 v[68:69], v[68:69], v[166:167] op_sel:[0,1] op_sel_hi:[1,1]
	v_pk_mul_f32 v[70:71], v[70:71], v[166:167] op_sel:[0,1] op_sel_hi:[1,1]
	v_pk_mul_f32 v[64:65], v[64:65], v[166:167] op_sel:[0,1] op_sel_hi:[1,1]
	v_pk_mul_f32 v[66:67], v[66:67], v[166:167] op_sel:[0,1] op_sel_hi:[1,1]
	v_max_f32_e32 v68, 0, v68
	v_max_f32_e32 v69, 0, v69
	v_max_f32_e32 v70, 0, v70
	v_max_f32_e32 v71, 0, v71
	v_max_f32_e32 v64, 0, v64
	v_max_f32_e32 v65, 0, v65
	v_max_f32_e32 v66, 0, v66
	v_max_f32_e32 v67, 0, v67
	v_pk_mul_f32 v[68:69], v[68:69], v[68:69]
	v_pk_mul_f32 v[70:71], v[70:71], v[70:71]
	v_pk_mul_f32 v[64:65], v[64:65], v[64:65]
	v_pk_mul_f32 v[66:67], v[66:67], v[66:67]
	v_cvt_pk_bf16_f32 v68, v68, v69
	v_cvt_pk_bf16_f32 v69, v70, v71
	v_cvt_pk_bf16_f32 v70, v64, v65
	v_cvt_pk_bf16_f32 v71, v66, v67
	s_add_u32 s100, s84, 0x60000
	s_addc_u32 s101, s85, 0
	global_store_dwordx4 v239, v[68:71], s[100:101] offset:256
	v_pk_mul_f32 v[60:61], v[60:61], v[168:169] op_sel_hi:[1,0]
	v_pk_mul_f32 v[62:63], v[62:63], v[168:169] op_sel_hi:[1,0]
	v_pk_mul_f32 v[56:57], v[56:57], v[168:169] op_sel_hi:[1,0]
	v_pk_mul_f32 v[58:59], v[58:59], v[168:169] op_sel_hi:[1,0]
	v_max_f32_e32 v60, 0, v60
	v_max_f32_e32 v61, 0, v61
	v_max_f32_e32 v62, 0, v62
	v_max_f32_e32 v63, 0, v63
	v_max_f32_e32 v56, 0, v56
	v_max_f32_e32 v57, 0, v57
	v_max_f32_e32 v58, 0, v58
	v_max_f32_e32 v59, 0, v59
	v_pk_mul_f32 v[60:61], v[60:61], v[60:61]
	v_pk_mul_f32 v[62:63], v[62:63], v[62:63]
	v_pk_mul_f32 v[56:57], v[56:57], v[56:57]
	v_pk_mul_f32 v[58:59], v[58:59], v[58:59]
	v_cvt_pk_bf16_f32 v60, v60, v61
	v_cvt_pk_bf16_f32 v61, v62, v63
	v_cvt_pk_bf16_f32 v62, v56, v57
	v_cvt_pk_bf16_f32 v63, v58, v59
	s_add_u32 s100, s84, 0x100000
	s_addc_u32 s101, s85, 0
	global_store_dwordx4 v239, v[60:63], s[100:101]
	v_pk_mul_f32 v[52:53], v[52:53], v[168:169] op_sel_hi:[1,0]
	v_pk_mul_f32 v[54:55], v[54:55], v[168:169] op_sel_hi:[1,0]
	v_pk_mul_f32 v[48:49], v[48:49], v[168:169] op_sel_hi:[1,0]
	v_pk_mul_f32 v[50:51], v[50:51], v[168:169] op_sel_hi:[1,0]
	v_max_f32_e32 v52, 0, v52
	v_max_f32_e32 v53, 0, v53
	v_max_f32_e32 v54, 0, v54
	v_max_f32_e32 v55, 0, v55
	v_max_f32_e32 v48, 0, v48
	v_max_f32_e32 v49, 0, v49
	v_max_f32_e32 v50, 0, v50
	v_max_f32_e32 v51, 0, v51
	v_pk_mul_f32 v[52:53], v[52:53], v[52:53]
	v_pk_mul_f32 v[54:55], v[54:55], v[54:55]
	v_pk_mul_f32 v[48:49], v[48:49], v[48:49]
	v_pk_mul_f32 v[50:51], v[50:51], v[50:51]
	v_cvt_pk_bf16_f32 v52, v52, v53
	v_cvt_pk_bf16_f32 v53, v54, v55
	v_cvt_pk_bf16_f32 v54, v48, v49
	v_cvt_pk_bf16_f32 v55, v50, v51
	s_add_u32 s100, s84, 0x100000
	s_addc_u32 s101, s85, 0
	global_store_dwordx4 v239, v[52:55], s[100:101] offset:256
	v_pk_mul_f32 v[44:45], v[44:45], v[168:169] op_sel:[0,1] op_sel_hi:[1,1]
	v_pk_mul_f32 v[46:47], v[46:47], v[168:169] op_sel:[0,1] op_sel_hi:[1,1]
	v_pk_mul_f32 v[40:41], v[40:41], v[168:169] op_sel:[0,1] op_sel_hi:[1,1]
	v_pk_mul_f32 v[42:43], v[42:43], v[168:169] op_sel:[0,1] op_sel_hi:[1,1]
	v_max_f32_e32 v44, 0, v44
	v_max_f32_e32 v45, 0, v45
	v_max_f32_e32 v46, 0, v46
	v_max_f32_e32 v47, 0, v47
	v_max_f32_e32 v40, 0, v40
	v_max_f32_e32 v41, 0, v41
	v_max_f32_e32 v42, 0, v42
	v_max_f32_e32 v43, 0, v43
	v_pk_mul_f32 v[44:45], v[44:45], v[44:45]
	v_pk_mul_f32 v[46:47], v[46:47], v[46:47]
	v_pk_mul_f32 v[40:41], v[40:41], v[40:41]
	v_pk_mul_f32 v[42:43], v[42:43], v[42:43]
	v_cvt_pk_bf16_f32 v230, v44, v45
	v_cvt_pk_bf16_f32 v231, v46, v47
	v_cvt_pk_bf16_f32 v232, v40, v41
	v_cvt_pk_bf16_f32 v233, v42, v43
	v_pk_mul_f32 v[36:37], v[36:37], v[168:169] op_sel:[0,1] op_sel_hi:[1,1]
	v_pk_mul_f32 v[38:39], v[38:39], v[168:169] op_sel:[0,1] op_sel_hi:[1,1]
	v_pk_mul_f32 v[32:33], v[32:33], v[168:169] op_sel:[0,1] op_sel_hi:[1,1]
	v_pk_mul_f32 v[34:35], v[34:35], v[168:169] op_sel:[0,1] op_sel_hi:[1,1]
	v_max_f32_e32 v36, 0, v36
	v_max_f32_e32 v37, 0, v37
	v_max_f32_e32 v38, 0, v38
	v_max_f32_e32 v39, 0, v39
	v_max_f32_e32 v32, 0, v32
	v_max_f32_e32 v33, 0, v33
	v_max_f32_e32 v34, 0, v34
	v_max_f32_e32 v35, 0, v35
	v_pk_mul_f32 v[36:37], v[36:37], v[36:37]
	v_pk_mul_f32 v[38:39], v[38:39], v[38:39]
	v_pk_mul_f32 v[32:33], v[32:33], v[32:33]
	v_pk_mul_f32 v[34:35], v[34:35], v[34:35]
	v_cvt_pk_bf16_f32 v234, v36, v37
	v_cvt_pk_bf16_f32 v235, v38, v39
	v_cvt_pk_bf16_f32 v236, v32, v33
	v_cvt_pk_bf16_f32 v237, v34, v35
	v_pk_mul_f32 v[28:29], v[28:29], v[170:171] op_sel_hi:[1,0]
	v_pk_mul_f32 v[30:31], v[30:31], v[170:171] op_sel_hi:[1,0]
	v_pk_mul_f32 v[24:25], v[24:25], v[170:171] op_sel_hi:[1,0]
	v_pk_mul_f32 v[26:27], v[26:27], v[170:171] op_sel_hi:[1,0]
	v_max_f32_e32 v28, 0, v28
	v_max_f32_e32 v29, 0, v29
	v_max_f32_e32 v30, 0, v30
	v_max_f32_e32 v31, 0, v31
	v_max_f32_e32 v24, 0, v24
	v_max_f32_e32 v25, 0, v25
	v_max_f32_e32 v26, 0, v26
	v_max_f32_e32 v27, 0, v27
	v_pk_mul_f32 v[28:29], v[28:29], v[28:29]
	v_pk_mul_f32 v[30:31], v[30:31], v[30:31]
	v_pk_mul_f32 v[24:25], v[24:25], v[24:25]
	v_pk_mul_f32 v[26:27], v[26:27], v[26:27]
	v_cvt_pk_bf16_f32 v240, v28, v29
	v_cvt_pk_bf16_f32 v241, v30, v31
	v_cvt_pk_bf16_f32 v242, v24, v25
	v_cvt_pk_bf16_f32 v243, v26, v27
	v_pk_mul_f32 v[20:21], v[20:21], v[170:171] op_sel_hi:[1,0]
	v_pk_mul_f32 v[22:23], v[22:23], v[170:171] op_sel_hi:[1,0]
	v_pk_mul_f32 v[16:17], v[16:17], v[170:171] op_sel_hi:[1,0]
	v_pk_mul_f32 v[18:19], v[18:19], v[170:171] op_sel_hi:[1,0]
	v_max_f32_e32 v20, 0, v20
	v_max_f32_e32 v21, 0, v21
	v_max_f32_e32 v22, 0, v22
	v_max_f32_e32 v23, 0, v23
	v_max_f32_e32 v16, 0, v16
	v_max_f32_e32 v17, 0, v17
	v_max_f32_e32 v18, 0, v18
	v_max_f32_e32 v19, 0, v19
	v_pk_mul_f32 v[20:21], v[20:21], v[20:21]
	v_pk_mul_f32 v[22:23], v[22:23], v[22:23]
	v_pk_mul_f32 v[16:17], v[16:17], v[16:17]
	v_pk_mul_f32 v[18:19], v[18:19], v[18:19]
	v_cvt_pk_bf16_f32 v244, v20, v21
	v_cvt_pk_bf16_f32 v245, v22, v23
	v_cvt_pk_bf16_f32 v246, v16, v17
	v_cvt_pk_bf16_f32 v247, v18, v19
	v_pk_mul_f32 v[12:13], v[12:13], v[170:171] op_sel:[0,1] op_sel_hi:[1,1]
	v_pk_mul_f32 v[14:15], v[14:15], v[170:171] op_sel:[0,1] op_sel_hi:[1,1]
	v_pk_mul_f32 v[8:9], v[8:9], v[170:171] op_sel:[0,1] op_sel_hi:[1,1]
	v_pk_mul_f32 v[10:11], v[10:11], v[170:171] op_sel:[0,1] op_sel_hi:[1,1]
	v_max_f32_e32 v12, 0, v12
	v_max_f32_e32 v13, 0, v13
	v_max_f32_e32 v14, 0, v14
	v_max_f32_e32 v15, 0, v15
	v_max_f32_e32 v8, 0, v8
	v_max_f32_e32 v9, 0, v9
	v_max_f32_e32 v10, 0, v10
	v_max_f32_e32 v11, 0, v11
	v_pk_mul_f32 v[12:13], v[12:13], v[12:13]
	v_pk_mul_f32 v[14:15], v[14:15], v[14:15]
	v_pk_mul_f32 v[8:9], v[8:9], v[8:9]
	v_pk_mul_f32 v[10:11], v[10:11], v[10:11]
	v_cvt_pk_bf16_f32 v248, v12, v13
	v_cvt_pk_bf16_f32 v249, v14, v15
	v_cvt_pk_bf16_f32 v250, v8, v9
	v_cvt_pk_bf16_f32 v251, v10, v11
	v_pk_mul_f32 v[4:5], v[4:5], v[170:171] op_sel:[0,1] op_sel_hi:[1,1]
	v_pk_mul_f32 v[6:7], v[6:7], v[170:171] op_sel:[0,1] op_sel_hi:[1,1]
	v_pk_mul_f32 v[0:1], v[0:1], v[170:171] op_sel:[0,1] op_sel_hi:[1,1]
	v_pk_mul_f32 v[2:3], v[2:3], v[170:171] op_sel:[0,1] op_sel_hi:[1,1]
	v_max_f32_e32 v4, 0, v4
	v_max_f32_e32 v5, 0, v5
	v_max_f32_e32 v6, 0, v6
	v_max_f32_e32 v7, 0, v7
	v_max_f32_e32 v0, 0, v0
	v_max_f32_e32 v1, 0, v1
	v_max_f32_e32 v2, 0, v2
	v_max_f32_e32 v3, 0, v3
	v_pk_mul_f32 v[4:5], v[4:5], v[4:5]
	v_pk_mul_f32 v[6:7], v[6:7], v[6:7]
	v_pk_mul_f32 v[0:1], v[0:1], v[0:1]
	v_pk_mul_f32 v[2:3], v[2:3], v[2:3]
	v_cvt_pk_bf16_f32 v252, v4, v5
	v_cvt_pk_bf16_f32 v253, v6, v7
	v_cvt_pk_bf16_f32 v254, v0, v1
	v_cvt_pk_bf16_f32 v255, v2, v3
	s_mov_b64 s[56:57], s[54:55]
	s_and_b64 vcc, exec, s[8:9]
	s_mov_b32 s67, s38
	s_mov_b32 s10, s50
	s_mov_b64 s[12:13], s[52:53]
	s_mov_b64 s[98:99], s[84:85]
	s_mov_b32 s32, 1
	s_cbranch_vccz .LBB0_980
	s_add_u32 s100, s84, 0x120000
	s_addc_u32 s101, s85, 0
	global_store_dwordx4 v239, v[230:233], s[100:101]
	s_add_u32 s100, s84, 0x120000
	s_addc_u32 s101, s85, 0
	global_store_dwordx4 v239, v[234:237], s[100:101] offset:256
	s_add_u32 s100, s84, 0x140000
	s_addc_u32 s101, s85, 0
	global_store_dwordx4 v239, v[240:243], s[100:101]
	s_add_u32 s100, s84, 0x140000
	s_addc_u32 s101, s85, 0
	global_store_dwordx4 v239, v[244:247], s[100:101] offset:256
	s_add_u32 s100, s84, 0x160000
	s_addc_u32 s101, s85, 0
	global_store_dwordx4 v239, v[248:251], s[100:101]
	s_add_u32 s100, s84, 0x160000
	s_addc_u32 s101, s85, 0
	global_store_dwordx4 v239, v[252:255], s[100:101] offset:256
	s_waitcnt vmcnt(0)
	s_cmpk_gt_u32 s0, 0xff
	s_cbranch_scc1 .LBB0_991
	s_barrier

.LBB0_1137:
	s_add_u32 s52, s14, 0x7a00000
	s_addc_u32 s53, s15, 0
	s_add_u32 s54, s14, 0x1fe80000
	s_addc_u32 s55, s15, 0
	s_lshl_b32 s45, s45, 5
	s_mov_b64 s[56:57], 0x80
	s_and_b32 s58, s45, 0x60
	s_add_i32 m0, s34, 0x18000
	v_lshl_add_u64 v[6:7], v[6:7], 0, s[56:57]
	s_lshl_b32 s11, s9, 13
	s_lshl_b32 s47, s58, 7
	s_waitcnt vmcnt(4)
	s_barrier
	global_load_lds_dwordx4 v[6:7], off
	v_lshl_add_u64 v[4:5], v[4:5], 0, s[56:57]
	s_add_i32 m0, s34, 0x1a000
	s_add_i32 s45, s34, 0x8000
	s_add_i32 s46, s34, 0xa000
	global_load_lds_dwordx4 v[4:5], off
	v_lshl_add_u64 v[2:3], v[2:3], 0, s[56:57]
	s_mov_b32 m0, s45
	s_add_u32 s48, s66, 0x40080
	global_load_lds_dwordx4 v[2:3], off
	v_lshl_add_u64 v[0:1], v[0:1], 0, s[56:57]
	s_mov_b32 m0, s46
	s_addc_u32 s49, s67, 0
	global_load_lds_dwordx4 v[0:1], off
	s_add_i32 m0, s34, 0x1c000
	v_lshl_add_u64 v[0:1], s[48:49], 0, v[132:133]
	global_load_lds_dwordx4 v[0:1], off
	v_lshl_add_u64 v[0:1], s[48:49], 0, v[128:129]
	s_add_i32 m0, s34, 0x1e000
	s_add_i32 s49, 0, 0x10000
	global_load_lds_dwordx4 v[0:1], off
	v_lshrrev_b32_e32 v1, 1, v9
	v_and_b32_e32 v1, 24, v1
	v_and_b32_e32 v0, 15, v9
	v_lshlrev_b32_e32 v2, 1, v1
	s_waitcnt vmcnt(0)
	v_lshl_or_b32 v149, s9, 6, v0
	v_lshl_or_b32 v0, v0, 6, v2
	v_lshlrev_b32_e32 v2, 2, v9
	v_and_b32_e32 v2, 32, v2
	v_bitop3_b32 v3, v0, s11, v2 bitop3:0xde
	v_bitop3_b32 v157, v0, s47, v2 bitop3:0xde
	v_lshlrev_b32_e32 v0, 14, v13
	v_and_b32_e32 v0, 0xffff8000, v0
	v_or_b32_e32 v158, s58, v1
	v_lshl_add_u32 v0, v12, 11, v0
	v_and_b32_e32 v1, 1, v13
	v_lshl_or_b32 v0, v1, 6, v0
	v_lshl_add_u32 v136, v14, 1, v0
	v_lshlrev_b32_e32 v0, 14, v8
	v_and_b32_e32 v0, 0xffff8000, v0
	s_waitcnt vmcnt(6)
	v_lshl_add_u32 v0, v10, 11, v0
	v_and_b32_e32 v1, 1, v8
	v_lshl_or_b32 v0, v1, 6, v0
	s_add_i32 s70, 0, 0x14000
	s_sext_i32_i8 s73, s8
	s_ashr_i32 s47, s22, 31
	s_mov_b32 s48, s22
	v_mov_b32_e32 v137, v133
	v_lshl_add_u32 v138, v11, 1, v0
	v_mov_b32_e32 v139, v133
	v_mov_b64_e32 v[140:141], 0x680
	v_mov_b64_e32 v[142:143], 0x67f
	v_add_u32_e32 v159, s49, v157
	v_add_u32_e32 v160, 0, v3
	v_add_u32_e32 v161, s70, v157
	v_mov_b32_e32 v162, 0x358637bd
	s_mov_b32 s71, 0x800000
	s_movk_i32 s72, 0x1a00
	s_barrier
	s_mov_b32 s32, 0
	v_mul_u32_u24_e32 v239, 0x1a00, v149
	v_lshl_add_u32 v239, v158, 1, v239

.LBB0_1141:
	ds_read_b128 v[144:147], v159
	ds_read_b128 v[150:153], v159 offset:1024
	ds_read_b128 v[164:167], v159 offset:2048
	ds_read_b128 v[168:171], v159 offset:3072
	s_add_u32 s66, s12, 0xfffc0080
	s_addc_u32 s67, s13, -1
	s_cmp_eq_u32 s77, 12
	s_cselect_b32 s69, s11, s67
	s_cselect_b32 s68, s61, s66
	s_cselect_b32 s67, s59, s76
	s_cselect_b32 s66, s74, s75
	v_lshl_add_u64 v[154:155], s[12:13], 0, v[136:137]
	s_add_i32 m0, s34, 0xc000
	ds_read_b128 v[172:175], v160
	ds_read_b128 v[176:179], v160 offset:1024
	ds_read_b128 v[180:183], v160 offset:2048
	ds_read_b128 v[184:187], v160 offset:3072
	ds_read_b128 v[188:191], v160 offset:4096
	ds_read_b128 v[192:195], v160 offset:5120
	ds_read_b128 v[196:199], v160 offset:6144
	ds_read_b128 v[200:203], v160 offset:7168
	global_load_lds_dwordx4 v[154:155], off
	v_lshl_add_u64 v[154:155], s[12:13], 0, v[138:139]
	s_add_i32 m0, s34, 0xe000
	s_nop 0
	global_load_lds_dwordx4 v[154:155], off
	s_waitcnt lgkmcnt(8)
	s_barrier
	s_waitcnt lgkmcnt(0)
	s_setprio 1
	s_waitcnt lgkmcnt(0)
	v_mfma_f32_16x16x32_bf16 v[124:127], v[144:147], v[172:175], v[124:127]
	v_mfma_f32_16x16x32_bf16 v[120:123], v[164:167], v[172:175], v[120:123]
	v_mfma_f32_16x16x32_bf16 v[116:119], v[144:147], v[180:183], v[116:119]
	v_mfma_f32_16x16x32_bf16 v[108:111], v[164:167], v[180:183], v[108:111]
	v_mfma_f32_16x16x32_bf16 v[100:103], v[144:147], v[188:191], v[100:103]
	v_mfma_f32_16x16x32_bf16 v[92:95], v[164:167], v[188:191], v[92:95]
	v_mfma_f32_16x16x32_bf16 v[84:87], v[144:147], v[196:199], v[84:87]
	v_mfma_f32_16x16x32_bf16 v[76:79], v[164:167], v[196:199], v[76:79]
	v_mfma_f32_16x16x32_bf16 v[124:127], v[150:153], v[176:179], v[124:127]
	v_mfma_f32_16x16x32_bf16 v[120:123], v[168:171], v[176:179], v[120:123]
	v_mfma_f32_16x16x32_bf16 v[116:119], v[150:153], v[184:187], v[116:119]
	v_mfma_f32_16x16x32_bf16 v[108:111], v[168:171], v[184:187], v[108:111]
	v_mfma_f32_16x16x32_bf16 v[100:103], v[150:153], v[192:195], v[100:103]
	v_mfma_f32_16x16x32_bf16 v[92:95], v[168:171], v[192:195], v[92:95]
	v_mfma_f32_16x16x32_bf16 v[84:87], v[150:153], v[200:203], v[84:87]
	v_mfma_f32_16x16x32_bf16 v[76:79], v[168:171], v[200:203], v[76:79]
	s_setprio 0
	s_barrier
	s_add_i32 s78, s49, s20
	v_lshl_add_u64 v[154:155], s[66:67], 0, v[132:133]
	s_mov_b32 m0, s78
	ds_read_b128 v[206:209], v161
	ds_read_b128 v[210:213], v161 offset:1024
	ds_read_b128 v[214:217], v161 offset:2048
	ds_read_b128 v[218:221], v161 offset:3072
	global_load_lds_dwordx4 v[154:155], off
	v_lshl_add_u64 v[222:223], s[66:67], 0, v[128:129]
	s_add_i32 m0, s78, 0x2000
	s_nop 0
	global_load_lds_dwordx4 v[222:223], off
	s_barrier
	s_waitcnt lgkmcnt(0)
	s_setprio 1
	s_waitcnt lgkmcnt(0)
	v_mfma_f32_16x16x32_bf16 v[112:115], v[206:209], v[172:175], v[112:115]
	v_mfma_f32_16x16x32_bf16 v[104:107], v[214:217], v[172:175], v[104:107]
	v_mfma_f32_16x16x32_bf16 v[96:99], v[206:209], v[180:183], v[96:99]
	v_mfma_f32_16x16x32_bf16 v[88:91], v[214:217], v[180:183], v[88:91]
	v_mfma_f32_16x16x32_bf16 v[80:83], v[206:209], v[188:191], v[80:83]
	v_mfma_f32_16x16x32_bf16 v[72:75], v[214:217], v[188:191], v[72:75]
	v_mfma_f32_16x16x32_bf16 v[68:71], v[206:209], v[196:199], v[68:71]
	v_mfma_f32_16x16x32_bf16 v[64:67], v[214:217], v[196:199], v[64:67]
	v_mfma_f32_16x16x32_bf16 v[112:115], v[210:213], v[176:179], v[112:115]
	v_mfma_f32_16x16x32_bf16 v[104:107], v[218:221], v[176:179], v[104:107]
	v_mfma_f32_16x16x32_bf16 v[96:99], v[210:213], v[184:187], v[96:99]
	v_mfma_f32_16x16x32_bf16 v[88:91], v[218:221], v[184:187], v[88:91]
	v_mfma_f32_16x16x32_bf16 v[80:83], v[210:213], v[192:195], v[80:83]
	v_mfma_f32_16x16x32_bf16 v[72:75], v[218:221], v[192:195], v[72:75]
	v_mfma_f32_16x16x32_bf16 v[68:71], v[210:213], v[200:203], v[68:71]
	v_mfma_f32_16x16x32_bf16 v[64:67], v[218:221], v[200:203], v[64:67]
	s_setprio 0
	s_mov_b32 m0, s34
	v_lshl_add_u64 v[224:225], s[68:69], 0, v[134:135]
	s_barrier
	ds_read_b128 v[172:175], v160 offset:16384
	ds_read_b128 v[176:179], v160 offset:17408
	ds_read_b128 v[180:183], v160 offset:18432
	ds_read_b128 v[184:187], v160 offset:19456
	ds_read_b128 v[188:191], v160 offset:20480
	ds_read_b128 v[192:195], v160 offset:21504
	ds_read_b128 v[196:199], v160 offset:22528
	ds_read_b128 v[200:203], v160 offset:23552
	global_load_lds_dwordx4 v[224:225], off
	v_lshl_add_u64 v[226:227], s[68:69], 0, v[130:131]
	s_mov_b32 m0, s35
	s_nop 0
	global_load_lds_dwordx4 v[226:227], off
	s_barrier
	s_waitcnt lgkmcnt(0)
	s_setprio 1
	s_waitcnt lgkmcnt(0)
	v_mfma_f32_16x16x32_bf16 v[60:63], v[144:147], v[172:175], v[60:63]
	v_mfma_f32_16x16x32_bf16 v[56:59], v[164:167], v[172:175], v[56:59]
	v_mfma_f32_16x16x32_bf16 v[52:55], v[144:147], v[180:183], v[52:55]
	v_mfma_f32_16x16x32_bf16 v[44:47], v[164:167], v[180:183], v[44:47]
	v_mfma_f32_16x16x32_bf16 v[36:39], v[144:147], v[188:191], v[36:39]
	v_mfma_f32_16x16x32_bf16 v[28:31], v[164:167], v[188:191], v[28:31]
	v_mfma_f32_16x16x32_bf16 v[20:23], v[144:147], v[196:199], v[20:23]
	v_mfma_f32_16x16x32_bf16 v[12:15], v[164:167], v[196:199], v[12:15]
	v_mfma_f32_16x16x32_bf16 v[60:63], v[150:153], v[176:179], v[60:63]
	v_mfma_f32_16x16x32_bf16 v[56:59], v[168:171], v[176:179], v[56:59]
	v_mfma_f32_16x16x32_bf16 v[52:55], v[150:153], v[184:187], v[52:55]
	v_mfma_f32_16x16x32_bf16 v[44:47], v[168:171], v[184:187], v[44:47]
	v_mfma_f32_16x16x32_bf16 v[36:39], v[150:153], v[192:195], v[36:39]
	v_mfma_f32_16x16x32_bf16 v[28:31], v[168:171], v[192:195], v[28:31]
	v_mfma_f32_16x16x32_bf16 v[20:23], v[150:153], v[200:203], v[20:23]
	v_mfma_f32_16x16x32_bf16 v[12:15], v[168:171], v[200:203], v[12:15]
	s_setprio 0
	s_barrier
	s_add_u32 s78, s66, 0x40000
	s_addc_u32 s79, s67, 0
	s_add_i32 s80, s70, s20
	v_lshl_add_u64 v[144:145], s[78:79], 0, v[132:133]
	s_mov_b32 m0, s80
	s_nop 0
	global_load_lds_dwordx4 v[144:145], off
	v_lshl_add_u64 v[144:145], s[78:79], 0, v[128:129]
	s_add_i32 m0, s80, 0x2000
	s_nop 0
	global_load_lds_dwordx4 v[144:145], off
	s_waitcnt vmcnt(6)
	s_cmp_gt_u32 s77, 6
	s_cbranch_scc1 .Lds_P8_a_done
	s_cmp_eq_u32 s77, 6
	s_cbranch_scc1 .Lds_P8_a_pf
	s_cmp_eq_u32 s32, 0
	s_cbranch_scc1 .Lds_P8_a_done
	s_cmp_eq_u32 s77, 0
	s_cbranch_scc1 .Lds_P8_a_0
	s_cmp_eq_u32 s77, 2
	s_cbranch_scc1 .Lds_P8_a_1
	s_add_u32 s100, s98, 0x11e000
	s_addc_u32 s101, s99, 0
	global_store_dwordx4 v239, v[248:251], s[100:101]
	s_branch .Lds_P8_a_done
.Lds_P8_a_1:
	s_add_u32 s100, s98, 0x104000
	s_addc_u32 s101, s99, 0
	global_store_dwordx4 v239, v[240:243], s[100:101]
	s_branch .Lds_P8_a_done
.Lds_P8_a_0:
	s_add_u32 s100, s98, 0xea000
	s_addc_u32 s101, s99, 0
	global_store_dwordx4 v239, v[230:233], s[100:101]
	s_branch .Lds_P8_a_done
.Lds_P8_a_pf:
	s_lshl_b32 s82, s10, 11
	s_add_u32 s100, s54, s82
	s_addc_u32 s101, s55, 0
	v_lshlrev_b32_e32 v252, 3, v149
	global_load_dwordx2 v[230:231], v252, s[100:101]
	global_load_dwordx2 v[232:233], v252, s[100:101] offset:128
	global_load_dwordx2 v[234:235], v252, s[100:101] offset:256
	global_load_dwordx2 v[236:237], v252, s[100:101] offset:384
	global_load_dwordx2 v[240:241], v252, s[100:101] offset:1024
	global_load_dwordx2 v[242:243], v252, s[100:101] offset:1152
	global_load_dwordx2 v[244:245], v252, s[100:101] offset:1280
	global_load_dwordx2 v[246:247], v252, s[100:101] offset:1408
.Lds_P8_a_done:
	s_barrier
	s_setprio 1
	v_mfma_f32_16x16x32_bf16 v[48:51], v[206:209], v[172:175], v[48:51]
	v_mfma_f32_16x16x32_bf16 v[40:43], v[214:217], v[172:175], v[40:43]
	v_mfma_f32_16x16x32_bf16 v[32:35], v[206:209], v[180:183], v[32:35]
	v_mfma_f32_16x16x32_bf16 v[24:27], v[214:217], v[180:183], v[24:27]
	v_mfma_f32_16x16x32_bf16 v[16:19], v[206:209], v[188:191], v[16:19]
	v_mfma_f32_16x16x32_bf16 v[8:11], v[214:217], v[188:191], v[8:11]
	v_mfma_f32_16x16x32_bf16 v[4:7], v[206:209], v[196:199], v[4:7]
	v_mfma_f32_16x16x32_bf16 v[0:3], v[214:217], v[196:199], v[0:3]
	v_mfma_f32_16x16x32_bf16 v[48:51], v[210:213], v[176:179], v[48:51]
	v_mfma_f32_16x16x32_bf16 v[40:43], v[218:221], v[176:179], v[40:43]
	v_mfma_f32_16x16x32_bf16 v[32:35], v[210:213], v[184:187], v[32:35]
	v_mfma_f32_16x16x32_bf16 v[24:27], v[218:221], v[184:187], v[24:27]
	v_mfma_f32_16x16x32_bf16 v[16:19], v[210:213], v[192:195], v[16:19]
	v_mfma_f32_16x16x32_bf16 v[8:11], v[218:221], v[192:195], v[8:11]
	v_mfma_f32_16x16x32_bf16 v[4:7], v[210:213], v[200:203], v[4:7]
	v_mfma_f32_16x16x32_bf16 v[0:3], v[218:221], v[200:203], v[0:3]
	s_setprio 0
	s_add_i32 s78, 0, 0x18000
	v_add_u32_e32 v148, s78, v157
	s_barrier
	ds_read_b128 v[144:147], v148
	ds_read_b128 v[150:153], v148 offset:1024
	ds_read_b128 v[164:167], v148 offset:2048
	ds_read_b128 v[168:171], v148 offset:3072
	s_add_u32 s68, s68, 0x40000
	s_addc_u32 s69, s69, 0
	s_mov_b32 m0, s42
	v_lshl_add_u64 v[206:207], s[68:69], 0, v[134:135]
	ds_read_b128 v[172:175], v160 offset:32768
	ds_read_b128 v[176:179], v160 offset:33792
	ds_read_b128 v[180:183], v160 offset:34816
	ds_read_b128 v[184:187], v160 offset:35840
	ds_read_b128 v[188:191], v160 offset:36864
	ds_read_b128 v[192:195], v160 offset:37888
	ds_read_b128 v[196:199], v160 offset:38912
	ds_read_b128 v[200:203], v160 offset:39936
	global_load_lds_dwordx4 v[206:207], off
	v_lshl_add_u64 v[206:207], s[68:69], 0, v[130:131]
	s_mov_b32 m0, s43
	s_nop 0
	global_load_lds_dwordx4 v[206:207], off
	s_waitcnt lgkmcnt(8)
	s_barrier
	s_waitcnt lgkmcnt(0)
	s_setprio 1
	s_waitcnt lgkmcnt(0)
	v_mfma_f32_16x16x32_bf16 v[124:127], v[144:147], v[172:175], v[124:127]
	v_mfma_f32_16x16x32_bf16 v[120:123], v[164:167], v[172:175], v[120:123]
	v_mfma_f32_16x16x32_bf16 v[116:119], v[144:147], v[180:183], v[116:119]
	v_mfma_f32_16x16x32_bf16 v[108:111], v[164:167], v[180:183], v[108:111]
	v_mfma_f32_16x16x32_bf16 v[100:103], v[144:147], v[188:191], v[100:103]
	v_mfma_f32_16x16x32_bf16 v[92:95], v[164:167], v[188:191], v[92:95]
	v_mfma_f32_16x16x32_bf16 v[84:87], v[144:147], v[196:199], v[84:87]
	v_mfma_f32_16x16x32_bf16 v[76:79], v[164:167], v[196:199], v[76:79]
	v_mfma_f32_16x16x32_bf16 v[124:127], v[150:153], v[176:179], v[124:127]
	v_mfma_f32_16x16x32_bf16 v[120:123], v[168:171], v[176:179], v[120:123]
	v_mfma_f32_16x16x32_bf16 v[116:119], v[150:153], v[184:187], v[116:119]
	v_mfma_f32_16x16x32_bf16 v[108:111], v[168:171], v[184:187], v[108:111]
	v_mfma_f32_16x16x32_bf16 v[100:103], v[150:153], v[192:195], v[100:103]
	v_mfma_f32_16x16x32_bf16 v[92:95], v[168:171], v[192:195], v[92:95]
	v_mfma_f32_16x16x32_bf16 v[84:87], v[150:153], v[200:203], v[84:87]
	v_mfma_f32_16x16x32_bf16 v[76:79], v[168:171], v[200:203], v[76:79]
	s_setprio 0
	s_barrier
	s_add_i32 s68, 0, 0x1c000
	s_add_i32 s69, s78, s20
	v_add_u32_e32 v148, s68, v157
	v_lshl_add_u64 v[154:155], v[154:155], 0, s[56:57]
	s_mov_b32 m0, s69
	ds_read_b128 v[206:209], v148
	ds_read_b128 v[210:213], v148 offset:1024
	ds_read_b128 v[214:217], v148 offset:2048
	ds_read_b128 v[218:221], v148 offset:3072
	global_load_lds_dwordx4 v[154:155], off
	v_lshl_add_u64 v[154:155], v[222:223], 0, s[56:57]
	s_add_i32 m0, s69, 0x2000
	s_nop 0
	global_load_lds_dwordx4 v[154:155], off
	s_barrier
	s_waitcnt lgkmcnt(0)
	s_setprio 1
	s_waitcnt lgkmcnt(0)
	v_mfma_f32_16x16x32_bf16 v[112:115], v[206:209], v[172:175], v[112:115]
	v_mfma_f32_16x16x32_bf16 v[104:107], v[214:217], v[172:175], v[104:107]
	v_mfma_f32_16x16x32_bf16 v[96:99], v[206:209], v[180:183], v[96:99]
	v_mfma_f32_16x16x32_bf16 v[88:91], v[214:217], v[180:183], v[88:91]
	v_mfma_f32_16x16x32_bf16 v[80:83], v[206:209], v[188:191], v[80:83]
	v_mfma_f32_16x16x32_bf16 v[72:75], v[214:217], v[188:191], v[72:75]
	v_mfma_f32_16x16x32_bf16 v[68:71], v[206:209], v[196:199], v[68:71]
	v_mfma_f32_16x16x32_bf16 v[64:67], v[214:217], v[196:199], v[64:67]
	v_mfma_f32_16x16x32_bf16 v[112:115], v[210:213], v[176:179], v[112:115]
	v_mfma_f32_16x16x32_bf16 v[104:107], v[218:221], v[176:179], v[104:107]
	v_mfma_f32_16x16x32_bf16 v[96:99], v[210:213], v[184:187], v[96:99]
	v_mfma_f32_16x16x32_bf16 v[88:91], v[218:221], v[184:187], v[88:91]
	v_mfma_f32_16x16x32_bf16 v[80:83], v[210:213], v[192:195], v[80:83]
	v_mfma_f32_16x16x32_bf16 v[72:75], v[218:221], v[192:195], v[72:75]
	v_mfma_f32_16x16x32_bf16 v[68:71], v[210:213], v[200:203], v[68:71]
	v_mfma_f32_16x16x32_bf16 v[64:67], v[218:221], v[200:203], v[64:67]
	s_setprio 0
	s_mov_b32 m0, s45
	v_lshl_add_u64 v[154:155], v[224:225], 0, s[56:57]
	s_barrier
	ds_read_b128 v[172:175], v160 offset:49152
	ds_read_b128 v[176:179], v160 offset:50176
	ds_read_b128 v[180:183], v160 offset:51200
	ds_read_b128 v[184:187], v160 offset:52224
	ds_read_b128 v[188:191], v160 offset:53248
	ds_read_b128 v[192:195], v160 offset:54272
	ds_read_b128 v[196:199], v160 offset:55296
	ds_read_b128 v[200:203], v160 offset:56320
	global_load_lds_dwordx4 v[154:155], off
	v_lshl_add_u64 v[154:155], v[226:227], 0, s[56:57]
	s_mov_b32 m0, s46
	s_nop 0
	global_load_lds_dwordx4 v[154:155], off
	s_barrier
	s_waitcnt lgkmcnt(0)
	s_setprio 1
	s_waitcnt lgkmcnt(0)
	v_mfma_f32_16x16x32_bf16 v[60:63], v[144:147], v[172:175], v[60:63]
	v_mfma_f32_16x16x32_bf16 v[56:59], v[164:167], v[172:175], v[56:59]
	v_mfma_f32_16x16x32_bf16 v[52:55], v[144:147], v[180:183], v[52:55]
	v_mfma_f32_16x16x32_bf16 v[44:47], v[164:167], v[180:183], v[44:47]
	v_mfma_f32_16x16x32_bf16 v[36:39], v[144:147], v[188:191], v[36:39]
	v_mfma_f32_16x16x32_bf16 v[28:31], v[164:167], v[188:191], v[28:31]
	v_mfma_f32_16x16x32_bf16 v[20:23], v[144:147], v[196:199], v[20:23]
	v_mfma_f32_16x16x32_bf16 v[12:15], v[164:167], v[196:199], v[12:15]
	v_mfma_f32_16x16x32_bf16 v[60:63], v[150:153], v[176:179], v[60:63]
	v_mfma_f32_16x16x32_bf16 v[56:59], v[168:171], v[176:179], v[56:59]
	v_mfma_f32_16x16x32_bf16 v[52:55], v[150:153], v[184:187], v[52:55]
	v_mfma_f32_16x16x32_bf16 v[44:47], v[168:171], v[184:187], v[44:47]
	v_mfma_f32_16x16x32_bf16 v[36:39], v[150:153], v[192:195], v[36:39]
	v_mfma_f32_16x16x32_bf16 v[28:31], v[168:171], v[192:195], v[28:31]
	v_mfma_f32_16x16x32_bf16 v[20:23], v[150:153], v[200:203], v[20:23]
	v_mfma_f32_16x16x32_bf16 v[12:15], v[168:171], v[200:203], v[12:15]
	s_setprio 0
	s_barrier
	s_add_u32 s66, s66, 0x40080
	s_addc_u32 s67, s67, 0
	s_add_i32 s68, s68, s20
	v_lshl_add_u64 v[144:145], s[66:67], 0, v[132:133]
	s_mov_b32 m0, s68
	s_nop 0
	global_load_lds_dwordx4 v[144:145], off
	v_lshl_add_u64 v[144:145], s[66:67], 0, v[128:129]
	s_add_i32 m0, s68, 0x2000
	s_nop 0
	global_load_lds_dwordx4 v[144:145], off
	s_waitcnt vmcnt(6)
	s_cmp_gt_u32 s77, 4
	s_cbranch_scc1 .Lds_P8_b_done
	s_cmp_eq_u32 s32, 0
	s_cbranch_scc1 .Lds_P8_b_done
	s_cmp_eq_u32 s77, 0
	s_cbranch_scc1 .Lds_P8_b_0
	s_cmp_eq_u32 s77, 2
	s_cbranch_scc1 .Lds_P8_b_1
	s_add_u32 s100, s98, 0x11e000
	s_addc_u32 s101, s99, 0
	global_store_dwordx4 v239, v[252:255], s[100:101] offset:256
	s_branch .Lds_P8_b_done
.Lds_P8_b_1:
	s_add_u32 s100, s98, 0x104000
	s_addc_u32 s101, s99, 0
	global_store_dwordx4 v239, v[244:247], s[100:101] offset:256
	s_branch .Lds_P8_b_done
.Lds_P8_b_0:
	s_add_u32 s100, s98, 0xea000
	s_addc_u32 s101, s99, 0
	global_store_dwordx4 v239, v[234:237], s[100:101] offset:256
.Lds_P8_b_done:
	s_barrier
	s_setprio 1
	v_mfma_f32_16x16x32_bf16 v[48:51], v[206:209], v[172:175], v[48:51]
	v_mfma_f32_16x16x32_bf16 v[40:43], v[214:217], v[172:175], v[40:43]
	v_mfma_f32_16x16x32_bf16 v[32:35], v[206:209], v[180:183], v[32:35]
	v_mfma_f32_16x16x32_bf16 v[24:27], v[214:217], v[180:183], v[24:27]
	v_mfma_f32_16x16x32_bf16 v[16:19], v[206:209], v[188:191], v[16:19]
	v_mfma_f32_16x16x32_bf16 v[8:11], v[214:217], v[188:191], v[8:11]
	v_mfma_f32_16x16x32_bf16 v[4:7], v[206:209], v[196:199], v[4:7]
	v_mfma_f32_16x16x32_bf16 v[0:3], v[214:217], v[196:199], v[0:3]
	v_mfma_f32_16x16x32_bf16 v[48:51], v[210:213], v[176:179], v[48:51]
	v_mfma_f32_16x16x32_bf16 v[40:43], v[218:221], v[176:179], v[40:43]
	v_mfma_f32_16x16x32_bf16 v[32:35], v[210:213], v[184:187], v[32:35]
	v_mfma_f32_16x16x32_bf16 v[24:27], v[218:221], v[184:187], v[24:27]
	v_mfma_f32_16x16x32_bf16 v[16:19], v[210:213], v[192:195], v[16:19]
	v_mfma_f32_16x16x32_bf16 v[8:11], v[218:221], v[192:195], v[8:11]
	v_mfma_f32_16x16x32_bf16 v[4:7], v[210:213], v[200:203], v[4:7]
	v_mfma_f32_16x16x32_bf16 v[0:3], v[218:221], v[200:203], v[0:3]
	s_setprio 0
	s_add_i32 s77, s77, 2
	s_add_u32 s12, s12, 0x100
	s_addc_u32 s13, s13, 0
	s_add_u32 s75, s75, 0x100
	s_addc_u32 s76, s76, 0
	s_cmp_gt_u32 s77, 13
	s_barrier
	s_cbranch_scc0 .LBB0_1141
.Lepi_P8_start:
	s_mul_i32 s82, s10, 0x1a0000
	s_lshl_b32 s84, s73, 9
	s_add_u32 s82, s82, s84
	s_add_u32 s84, s52, s82
	s_addc_u32 s85, s53, 0
	v_mov_b32_e32 v144, 0x358637bd
	v_ffbh_u32_e32 v172, v231
	v_ffbh_u32_e32 v173, v233
	v_ffbh_u32_e32 v174, v235
	v_ffbh_u32_e32 v175, v237
	v_ffbh_u32_e32 v176, v241
	v_ffbh_u32_e32 v177, v243
	v_ffbh_u32_e32 v178, v245
	v_ffbh_u32_e32 v179, v247
	v_min_u32_e32 v172, 32, v172
	v_min_u32_e32 v173, 32, v173
	v_min_u32_e32 v174, 32, v174
	v_min_u32_e32 v175, 32, v175
	v_min_u32_e32 v176, 32, v176
	v_min_u32_e32 v177, 32, v177
	v_min_u32_e32 v178, 32, v178
	v_min_u32_e32 v179, 32, v179
	v_lshlrev_b64 v[230:231], v172, v[230:231]
	v_lshlrev_b64 v[232:233], v173, v[232:233]
	v_lshlrev_b64 v[234:235], v174, v[234:235]
	v_lshlrev_b64 v[236:237], v175, v[236:237]
	v_lshlrev_b64 v[240:241], v176, v[240:241]
	v_lshlrev_b64 v[242:243], v177, v[242:243]
	v_lshlrev_b64 v[244:245], v178, v[244:245]
	v_lshlrev_b64 v[246:247], v179, v[246:247]
	v_min_u32_e32 v230, 1, v230
	v_min_u32_e32 v232, 1, v232
	v_min_u32_e32 v234, 1, v234
	v_min_u32_e32 v236, 1, v236
	v_min_u32_e32 v240, 1, v240
	v_min_u32_e32 v242, 1, v242
	v_min_u32_e32 v244, 1, v244
	v_min_u32_e32 v246, 1, v246
	v_or_b32_e32 v231, v231, v230
	v_or_b32_e32 v233, v233, v232
	v_or_b32_e32 v235, v235, v234
	v_or_b32_e32 v237, v237, v236
	v_or_b32_e32 v241, v241, v240
	v_or_b32_e32 v243, v243, v242
	v_or_b32_e32 v245, v245, v244
	v_or_b32_e32 v247, v247, v246
	v_cvt_f32_u32_e32 v231, v231
	v_cvt_f32_u32_e32 v233, v233
	v_cvt_f32_u32_e32 v235, v235
	v_cvt_f32_u32_e32 v237, v237
	v_cvt_f32_u32_e32 v241, v241
	v_cvt_f32_u32_e32 v243, v243
	v_cvt_f32_u32_e32 v245, v245
	v_cvt_f32_u32_e32 v247, v247
	v_sub_u32_e32 v172, 32, v172
	v_sub_u32_e32 v173, 32, v173
	v_sub_u32_e32 v174, 32, v174
	v_sub_u32_e32 v175, 32, v175
	v_sub_u32_e32 v176, 32, v176
	v_sub_u32_e32 v177, 32, v177
	v_sub_u32_e32 v178, 32, v178
	v_sub_u32_e32 v179, 32, v179
	v_ldexp_f32 v231, v231, v172
	v_ldexp_f32 v233, v233, v173
	v_ldexp_f32 v235, v235, v174
	v_ldexp_f32 v237, v237, v175
	v_ldexp_f32 v241, v241, v176
	v_ldexp_f32 v243, v243, v177
	v_ldexp_f32 v245, v245, v178
	v_ldexp_f32 v247, v247, v179
	v_fmamk_f32 v231, v231, 0x2e800000, v144
	v_fmamk_f32 v233, v233, 0x2e800000, v144
	v_fmamk_f32 v235, v235, 0x2e800000, v144
	v_fmamk_f32 v237, v237, 0x2e800000, v144
	v_fmamk_f32 v241, v241, 0x2e800000, v144
	v_fmamk_f32 v243, v243, 0x2e800000, v144
	v_fmamk_f32 v245, v245, 0x2e800000, v144
	v_fmamk_f32 v247, v247, 0x2e800000, v144
	v_rsq_f32_e32 v164, v231
	v_rsq_f32_e32 v165, v233
	v_rsq_f32_e32 v166, v235
	v_rsq_f32_e32 v167, v237
	v_rsq_f32_e32 v168, v241
	v_rsq_f32_e32 v169, v243
	v_rsq_f32_e32 v170, v245
	v_rsq_f32_e32 v171, v247
	s_nop 0
	v_pk_mul_f32 v[124:125], v[124:125], v[164:165] op_sel_hi:[1,0]
	v_pk_mul_f32 v[126:127], v[126:127], v[164:165] op_sel_hi:[1,0]
	v_pk_mul_f32 v[120:121], v[120:121], v[164:165] op_sel_hi:[1,0]
	v_pk_mul_f32 v[122:123], v[122:123], v[164:165] op_sel_hi:[1,0]
	v_cvt_pk_bf16_f32 v124, v124, v125
	v_cvt_pk_bf16_f32 v125, v126, v127
	v_cvt_pk_bf16_f32 v126, v120, v121
	v_cvt_pk_bf16_f32 v127, v122, v123
	global_store_dwordx4 v239, v[124:127], s[84:85]
	v_pk_mul_f32 v[112:113], v[112:113], v[164:165] op_sel_hi:[1,0]
	v_pk_mul_f32 v[114:115], v[114:115], v[164:165] op_sel_hi:[1,0]
	v_pk_mul_f32 v[104:105], v[104:105], v[164:165] op_sel_hi:[1,0]
	v_pk_mul_f32 v[106:107], v[106:107], v[164:165] op_sel_hi:[1,0]
	v_cvt_pk_bf16_f32 v112, v112, v113
	v_cvt_pk_bf16_f32 v113, v114, v115
	v_cvt_pk_bf16_f32 v114, v104, v105
	v_cvt_pk_bf16_f32 v115, v106, v107
	global_store_dwordx4 v239, v[112:115], s[84:85] offset:256
	v_pk_mul_f32 v[116:117], v[116:117], v[164:165] op_sel:[0,1] op_sel_hi:[1,1]
	v_pk_mul_f32 v[118:119], v[118:119], v[164:165] op_sel:[0,1] op_sel_hi:[1,1]
	v_pk_mul_f32 v[108:109], v[108:109], v[164:165] op_sel:[0,1] op_sel_hi:[1,1]
	v_pk_mul_f32 v[110:111], v[110:111], v[164:165] op_sel:[0,1] op_sel_hi:[1,1]
	v_cvt_pk_bf16_f32 v116, v116, v117
	v_cvt_pk_bf16_f32 v117, v118, v119
	v_cvt_pk_bf16_f32 v118, v108, v109
	v_cvt_pk_bf16_f32 v119, v110, v111
	s_add_u32 s100, s84, 0x1a000
	s_addc_u32 s101, s85, 0
	global_store_dwordx4 v239, v[116:119], s[100:101]
	v_pk_mul_f32 v[96:97], v[96:97], v[164:165] op_sel:[0,1] op_sel_hi:[1,1]
	v_pk_mul_f32 v[98:99], v[98:99], v[164:165] op_sel:[0,1] op_sel_hi:[1,1]
	v_pk_mul_f32 v[88:89], v[88:89], v[164:165] op_sel:[0,1] op_sel_hi:[1,1]
	v_pk_mul_f32 v[90:91], v[90:91], v[164:165] op_sel:[0,1] op_sel_hi:[1,1]
	v_cvt_pk_bf16_f32 v96, v96, v97
	v_cvt_pk_bf16_f32 v97, v98, v99
	v_cvt_pk_bf16_f32 v98, v88, v89
	v_cvt_pk_bf16_f32 v99, v90, v91
	s_add_u32 s100, s84, 0x1a000
	s_addc_u32 s101, s85, 0
	global_store_dwordx4 v239, v[96:99], s[100:101] offset:256
	v_pk_mul_f32 v[100:101], v[100:101], v[166:167] op_sel_hi:[1,0]
	v_pk_mul_f32 v[102:103], v[102:103], v[166:167] op_sel_hi:[1,0]
	v_pk_mul_f32 v[92:93], v[92:93], v[166:167] op_sel_hi:[1,0]
	v_pk_mul_f32 v[94:95], v[94:95], v[166:167] op_sel_hi:[1,0]
	v_cvt_pk_bf16_f32 v100, v100, v101
	v_cvt_pk_bf16_f32 v101, v102, v103
	v_cvt_pk_bf16_f32 v102, v92, v93
	v_cvt_pk_bf16_f32 v103, v94, v95
	s_add_u32 s100, s84, 0x34000
	s_addc_u32 s101, s85, 0
	global_store_dwordx4 v239, v[100:103], s[100:101]
	v_pk_mul_f32 v[80:81], v[80:81], v[166:167] op_sel_hi:[1,0]
	v_pk_mul_f32 v[82:83], v[82:83], v[166:167] op_sel_hi:[1,0]
	v_pk_mul_f32 v[72:73], v[72:73], v[166:167] op_sel_hi:[1,0]
	v_pk_mul_f32 v[74:75], v[74:75], v[166:167] op_sel_hi:[1,0]
	v_cvt_pk_bf16_f32 v80, v80, v81
	v_cvt_pk_bf16_f32 v81, v82, v83
	v_cvt_pk_bf16_f32 v82, v72, v73
	v_cvt_pk_bf16_f32 v83, v74, v75
	s_add_u32 s100, s84, 0x34000
	s_addc_u32 s101, s85, 0
	global_store_dwordx4 v239, v[80:83], s[100:101] offset:256
	v_pk_mul_f32 v[84:85], v[84:85], v[166:167] op_sel:[0,1] op_sel_hi:[1,1]
	v_pk_mul_f32 v[86:87], v[86:87], v[166:167] op_sel:[0,1] op_sel_hi:[1,1]
	v_pk_mul_f32 v[76:77], v[76:77], v[166:167] op_sel:[0,1] op_sel_hi:[1,1]
	v_pk_mul_f32 v[78:79], v[78:79], v[166:167] op_sel:[0,1] op_sel_hi:[1,1]
	v_cvt_pk_bf16_f32 v84, v84, v85
	v_cvt_pk_bf16_f32 v85, v86, v87
	v_cvt_pk_bf16_f32 v86, v76, v77
	v_cvt_pk_bf16_f32 v87, v78, v79
	s_add_u32 s100, s84, 0x4e000
	s_addc_u32 s101, s85, 0
	global_store_dwordx4 v239, v[84:87], s[100:101]
	v_pk_mul_f32 v[68:69], v[68:69], v[166:167] op_sel:[0,1] op_sel_hi:[1,1]
	v_pk_mul_f32 v[70:71], v[70:71], v[166:167] op_sel:[0,1] op_sel_hi:[1,1]
	v_pk_mul_f32 v[64:65], v[64:65], v[166:167] op_sel:[0,1] op_sel_hi:[1,1]
	v_pk_mul_f32 v[66:67], v[66:67], v[166:167] op_sel:[0,1] op_sel_hi:[1,1]
	v_cvt_pk_bf16_f32 v68, v68, v69
	v_cvt_pk_bf16_f32 v69, v70, v71
	v_cvt_pk_bf16_f32 v70, v64, v65
	v_cvt_pk_bf16_f32 v71, v66, v67
	s_add_u32 s100, s84, 0x4e000
	s_addc_u32 s101, s85, 0
	global_store_dwordx4 v239, v[68:71], s[100:101] offset:256
	v_pk_mul_f32 v[60:61], v[60:61], v[168:169] op_sel_hi:[1,0]
	v_pk_mul_f32 v[62:63], v[62:63], v[168:169] op_sel_hi:[1,0]
	v_pk_mul_f32 v[56:57], v[56:57], v[168:169] op_sel_hi:[1,0]
	v_pk_mul_f32 v[58:59], v[58:59], v[168:169] op_sel_hi:[1,0]
	v_cvt_pk_bf16_f32 v60, v60, v61
	v_cvt_pk_bf16_f32 v61, v62, v63
	v_cvt_pk_bf16_f32 v62, v56, v57
	v_cvt_pk_bf16_f32 v63, v58, v59
	s_add_u32 s100, s84, 0xd0000
	s_addc_u32 s101, s85, 0
	global_store_dwordx4 v239, v[60:63], s[100:101]
	v_pk_mul_f32 v[48:49], v[48:49], v[168:169] op_sel_hi:[1,0]
	v_pk_mul_f32 v[50:51], v[50:51], v[168:169] op_sel_hi:[1,0]
	v_pk_mul_f32 v[40:41], v[40:41], v[168:169] op_sel_hi:[1,0]
	v_pk_mul_f32 v[42:43], v[42:43], v[168:169] op_sel_hi:[1,0]
	v_cvt_pk_bf16_f32 v48, v48, v49
	v_cvt_pk_bf16_f32 v49, v50, v51
	v_cvt_pk_bf16_f32 v50, v40, v41
	v_cvt_pk_bf16_f32 v51, v42, v43
	s_add_u32 s100, s84, 0xd0000
	s_addc_u32 s101, s85, 0
	global_store_dwordx4 v239, v[48:51], s[100:101] offset:256
	v_pk_mul_f32 v[52:53], v[52:53], v[168:169] op_sel:[0,1] op_sel_hi:[1,1]
	v_pk_mul_f32 v[54:55], v[54:55], v[168:169] op_sel:[0,1] op_sel_hi:[1,1]
	v_pk_mul_f32 v[44:45], v[44:45], v[168:169] op_sel:[0,1] op_sel_hi:[1,1]
	v_pk_mul_f32 v[46:47], v[46:47], v[168:169] op_sel:[0,1] op_sel_hi:[1,1]
	v_cvt_pk_bf16_f32 v230, v52, v53
	v_cvt_pk_bf16_f32 v231, v54, v55
	v_cvt_pk_bf16_f32 v232, v44, v45
	v_cvt_pk_bf16_f32 v233, v46, v47
	v_pk_mul_f32 v[32:33], v[32:33], v[168:169] op_sel:[0,1] op_sel_hi:[1,1]
	v_pk_mul_f32 v[34:35], v[34:35], v[168:169] op_sel:[0,1] op_sel_hi:[1,1]
	v_pk_mul_f32 v[24:25], v[24:25], v[168:169] op_sel:[0,1] op_sel_hi:[1,1]
	v_pk_mul_f32 v[26:27], v[26:27], v[168:169] op_sel:[0,1] op_sel_hi:[1,1]
	v_cvt_pk_bf16_f32 v234, v32, v33
	v_cvt_pk_bf16_f32 v235, v34, v35
	v_cvt_pk_bf16_f32 v236, v24, v25
	v_cvt_pk_bf16_f32 v237, v26, v27
	v_pk_mul_f32 v[36:37], v[36:37], v[170:171] op_sel_hi:[1,0]
	v_pk_mul_f32 v[38:39], v[38:39], v[170:171] op_sel_hi:[1,0]
	v_pk_mul_f32 v[28:29], v[28:29], v[170:171] op_sel_hi:[1,0]
	v_pk_mul_f32 v[30:31], v[30:31], v[170:171] op_sel_hi:[1,0]
	v_cvt_pk_bf16_f32 v240, v36, v37
	v_cvt_pk_bf16_f32 v241, v38, v39
	v_cvt_pk_bf16_f32 v242, v28, v29
	v_cvt_pk_bf16_f32 v243, v30, v31
	v_pk_mul_f32 v[16:17], v[16:17], v[170:171] op_sel_hi:[1,0]
	v_pk_mul_f32 v[18:19], v[18:19], v[170:171] op_sel_hi:[1,0]
	v_pk_mul_f32 v[8:9], v[8:9], v[170:171] op_sel_hi:[1,0]
	v_pk_mul_f32 v[10:11], v[10:11], v[170:171] op_sel_hi:[1,0]
	v_cvt_pk_bf16_f32 v244, v16, v17
	v_cvt_pk_bf16_f32 v245, v18, v19
	v_cvt_pk_bf16_f32 v246, v8, v9
	v_cvt_pk_bf16_f32 v247, v10, v11
	v_pk_mul_f32 v[20:21], v[20:21], v[170:171] op_sel:[0,1] op_sel_hi:[1,1]
	v_pk_mul_f32 v[22:23], v[22:23], v[170:171] op_sel:[0,1] op_sel_hi:[1,1]
	v_pk_mul_f32 v[12:13], v[12:13], v[170:171] op_sel:[0,1] op_sel_hi:[1,1]
	v_pk_mul_f32 v[14:15], v[14:15], v[170:171] op_sel:[0,1] op_sel_hi:[1,1]
	v_cvt_pk_bf16_f32 v248, v20, v21
	v_cvt_pk_bf16_f32 v249, v22, v23
	v_cvt_pk_bf16_f32 v250, v12, v13
	v_cvt_pk_bf16_f32 v251, v14, v15
	v_pk_mul_f32 v[4:5], v[4:5], v[170:171] op_sel:[0,1] op_sel_hi:[1,1]
	v_pk_mul_f32 v[6:7], v[6:7], v[170:171] op_sel:[0,1] op_sel_hi:[1,1]
	v_pk_mul_f32 v[0:1], v[0:1], v[170:171] op_sel:[0,1] op_sel_hi:[1,1]
	v_pk_mul_f32 v[2:3], v[2:3], v[170:171] op_sel:[0,1] op_sel_hi:[1,1]
	v_cvt_pk_bf16_f32 v252, v4, v5
	v_cvt_pk_bf16_f32 v253, v6, v7
	v_cvt_pk_bf16_f32 v254, v0, v1
	v_cvt_pk_bf16_f32 v255, v2, v3
	s_mov_b64 s[66:67], s[64:65]
	s_and_b64 vcc, exec, s[8:9]
	s_mov_b32 s73, s58
	s_mov_b64 s[12:13], s[62:63]
	s_mov_b32 s10, s60
	s_mov_b64 s[98:99], s[84:85]
	s_mov_b32 s32, 1
	s_cbranch_vccz .LBB0_1138
	s_add_u32 s100, s84, 0xea000
	s_addc_u32 s101, s85, 0
	global_store_dwordx4 v239, v[230:233], s[100:101]
	s_add_u32 s100, s84, 0xea000
	s_addc_u32 s101, s85, 0
	global_store_dwordx4 v239, v[234:237], s[100:101] offset:256
	s_add_u32 s100, s84, 0x104000
	s_addc_u32 s101, s85, 0
	global_store_dwordx4 v239, v[240:243], s[100:101]
	s_add_u32 s100, s84, 0x104000
	s_addc_u32 s101, s85, 0
	global_store_dwordx4 v239, v[244:247], s[100:101] offset:256
	s_add_u32 s100, s84, 0x11e000
	s_addc_u32 s101, s85, 0
	global_store_dwordx4 v239, v[248:251], s[100:101]
	s_add_u32 s100, s84, 0x11e000
	s_addc_u32 s101, s85, 0
	global_store_dwordx4 v239, v[252:255], s[100:101] offset:256
	s_waitcnt vmcnt(0)
	s_cmpk_gt_u32 s0, 0xff
	s_cbranch_scc1 .LBB0_1145
	s_barrier

.LBB0_1973:
	s_add_u32 s14, s12, 0x7a00000
	s_addc_u32 s15, s13, 0
	s_add_u32 s16, s12, 0x1fec0000
	s_addc_u32 s17, s13, 0
	s_lshl_b32 s18, s18, 5
	s_and_b32 s26, s18, 0x60
	s_mov_b64 s[18:19], 0x80
	s_add_i32 m0, s46, 0x18000
	v_lshl_add_u64 v[6:7], v[6:7], 0, s[18:19]
	s_lshl_b32 s9, s7, 13
	s_lshl_b32 s27, s26, 7
	s_waitcnt vmcnt(4)
	s_barrier
	global_load_lds_dwordx4 v[6:7], off
	v_lshl_add_u64 v[4:5], v[4:5], 0, s[18:19]
	s_add_i32 m0, s46, 0x1a000
	s_add_i32 s51, s46, 0x8000
	s_add_i32 s52, s46, 0xa000
	global_load_lds_dwordx4 v[4:5], off
	v_lshl_add_u64 v[2:3], v[2:3], 0, s[18:19]
	s_mov_b32 m0, s51
	s_add_u32 s24, s42, 0x40080
	global_load_lds_dwordx4 v[2:3], off
	v_lshl_add_u64 v[0:1], v[0:1], 0, s[18:19]
	s_mov_b32 m0, s52
	s_addc_u32 s25, s43, 0
	global_load_lds_dwordx4 v[0:1], off
	s_add_i32 m0, s46, 0x1c000
	v_lshl_add_u64 v[0:1], s[24:25], 0, v[130:131]
	global_load_lds_dwordx4 v[0:1], off
	v_lshl_add_u64 v[0:1], s[24:25], 0, v[134:135]
	s_add_i32 m0, s46, 0x1e000
	s_add_i32 s55, 0, 0x10000
	global_load_lds_dwordx4 v[0:1], off
	v_lshrrev_b32_e32 v1, 1, v8
	v_and_b32_e32 v1, 24, v1
	v_and_b32_e32 v0, 15, v8
	v_lshlrev_b32_e32 v2, 1, v1
	v_lshl_or_b32 v145, s7, 6, v0
	v_lshl_or_b32 v0, v0, 6, v2
	v_lshlrev_b32_e32 v2, 2, v8
	v_and_b32_e32 v2, 32, v2
	v_bitop3_b32 v3, v0, s9, v2 bitop3:0xde
	v_bitop3_b32 v149, v0, s27, v2 bitop3:0xde
	v_lshlrev_b32_e32 v0, 14, v9
	v_and_b32_e32 v0, 0xffff8000, v0
	v_or_b32_e32 v151, s26, v1
	v_lshl_add_u32 v0, v10, 11, v0
	v_and_b32_e32 v1, 1, v9
	v_lshl_or_b32 v0, v1, 6, v0
	v_lshl_add_u32 v136, v11, 1, v0
	v_lshlrev_b32_e32 v0, 14, v12
	v_and_b32_e32 v0, 0xffff8000, v0
	s_waitcnt vmcnt(6)
	v_lshl_add_u32 v0, v13, 11, v0
	v_and_b32_e32 v1, 1, v12
	v_lshl_or_b32 v0, v1, 6, v0
	s_add_i32 s56, 0, 0x14000
	s_sext_i32_i8 s62, s6
	s_ashr_i32 s53, s22, 31
	s_mov_b32 s54, s22
	v_mov_b32_e32 v137, v131
	v_lshl_add_u32 v138, v14, 1, v0
	v_mov_b32_e32 v139, v131
	v_mov_b64_e32 v[140:141], 0x800
	v_mov_b64_e32 v[142:143], 0x7ff
	v_add_u32_e32 v155, s55, v149
	v_add_u32_e32 v159, 0, v3
	v_add_u32_e32 v162, s56, v149
	v_mov_b32_e32 v163, 0x358637bd
	s_mov_b32 s57, 0x800000
	s_mov_b64 s[24:25], 0x100000
	s_mov_b32 s58, 0x100000
	s_mov_b64 s[26:27], 0x120000
	s_mov_b32 s59, 0x120000
	s_mov_b64 s[28:29], 0x140000
	s_mov_b32 s60, 0x140000
	s_mov_b64 s[30:31], 0x160000
	s_mov_b32 s61, 0x160000
	s_barrier
	s_mov_b32 s32, 0
	v_mul_u32_u24_e32 v239, 0x2000, v145
	v_lshl_add_u32 v239, v151, 1, v239

.LBB0_1981:
	ds_read_b128 v[164:167], v155
	ds_read_b128 v[168:171], v155 offset:1024
	ds_read_b128 v[172:175], v155 offset:2048
	ds_read_b128 v[176:179], v155 offset:3072
	s_add_u32 s42, s10, 0xfffc0080
	s_addc_u32 s43, s11, -1
	s_cmp_eq_u32 s66, 12
	s_cselect_b32 s45, s9, s43
	s_cselect_b32 s44, s37, s42
	s_cselect_b32 s43, s35, s65
	s_cselect_b32 s42, s63, s64
	v_lshl_add_u64 v[146:147], s[10:11], 0, v[136:137]
	s_add_i32 m0, s46, 0xc000
	ds_read_b128 v[180:183], v159
	ds_read_b128 v[184:187], v159 offset:1024
	ds_read_b128 v[188:191], v159 offset:2048
	ds_read_b128 v[192:195], v159 offset:3072
	ds_read_b128 v[196:199], v159 offset:4096
	ds_read_b128 v[200:203], v159 offset:5120
	ds_read_b128 v[206:209], v159 offset:6144
	ds_read_b128 v[210:213], v159 offset:7168
	global_load_lds_dwordx4 v[146:147], off
	v_lshl_add_u64 v[146:147], s[10:11], 0, v[138:139]
	s_add_i32 m0, s46, 0xe000
	s_nop 0
	global_load_lds_dwordx4 v[146:147], off
	s_waitcnt lgkmcnt(8)
	s_barrier
	s_waitcnt lgkmcnt(0)
	s_setprio 1
	s_waitcnt lgkmcnt(0)
	v_mfma_f32_16x16x32_bf16 v[124:127], v[164:167], v[180:183], v[124:127]
	v_mfma_f32_16x16x32_bf16 v[120:123], v[172:175], v[180:183], v[120:123]
	v_mfma_f32_16x16x32_bf16 v[108:111], v[164:167], v[188:191], v[108:111]
	v_mfma_f32_16x16x32_bf16 v[104:107], v[172:175], v[188:191], v[104:107]
	v_mfma_f32_16x16x32_bf16 v[92:95], v[164:167], v[196:199], v[92:95]
	v_mfma_f32_16x16x32_bf16 v[88:91], v[172:175], v[196:199], v[88:91]
	v_mfma_f32_16x16x32_bf16 v[76:79], v[164:167], v[206:209], v[76:79]
	v_mfma_f32_16x16x32_bf16 v[72:75], v[172:175], v[206:209], v[72:75]
	v_mfma_f32_16x16x32_bf16 v[124:127], v[168:171], v[184:187], v[124:127]
	v_mfma_f32_16x16x32_bf16 v[120:123], v[176:179], v[184:187], v[120:123]
	v_mfma_f32_16x16x32_bf16 v[108:111], v[168:171], v[192:195], v[108:111]
	v_mfma_f32_16x16x32_bf16 v[104:107], v[176:179], v[192:195], v[104:107]
	v_mfma_f32_16x16x32_bf16 v[92:95], v[168:171], v[200:203], v[92:95]
	v_mfma_f32_16x16x32_bf16 v[88:91], v[176:179], v[200:203], v[88:91]
	v_mfma_f32_16x16x32_bf16 v[76:79], v[168:171], v[210:213], v[76:79]
	v_mfma_f32_16x16x32_bf16 v[72:75], v[176:179], v[210:213], v[72:75]
	s_setprio 0
	s_barrier
	s_add_i32 s67, s55, s33
	v_lshl_add_u64 v[146:147], s[42:43], 0, v[130:131]
	s_mov_b32 m0, s67
	ds_read_b128 v[214:217], v162
	ds_read_b128 v[218:221], v162 offset:1024
	ds_read_b128 v[222:225], v162 offset:2048
	ds_read_b128 v[226:229], v162 offset:3072
	global_load_lds_dwordx4 v[146:147], off
	v_lshl_add_u64 v[152:153], s[42:43], 0, v[134:135]
	s_add_i32 m0, s67, 0x2000
	s_nop 0
	global_load_lds_dwordx4 v[152:153], off
	s_barrier
	s_waitcnt lgkmcnt(0)
	s_setprio 1
	s_waitcnt lgkmcnt(0)
	v_mfma_f32_16x16x32_bf16 v[116:119], v[214:217], v[180:183], v[116:119]
	v_mfma_f32_16x16x32_bf16 v[112:115], v[222:225], v[180:183], v[112:115]
	v_mfma_f32_16x16x32_bf16 v[100:103], v[214:217], v[188:191], v[100:103]
	v_mfma_f32_16x16x32_bf16 v[96:99], v[222:225], v[188:191], v[96:99]
	v_mfma_f32_16x16x32_bf16 v[84:87], v[214:217], v[196:199], v[84:87]
	v_mfma_f32_16x16x32_bf16 v[80:83], v[222:225], v[196:199], v[80:83]
	v_mfma_f32_16x16x32_bf16 v[68:71], v[214:217], v[206:209], v[68:71]
	v_mfma_f32_16x16x32_bf16 v[64:67], v[222:225], v[206:209], v[64:67]
	v_mfma_f32_16x16x32_bf16 v[116:119], v[218:221], v[184:187], v[116:119]
	v_mfma_f32_16x16x32_bf16 v[112:115], v[226:229], v[184:187], v[112:115]
	v_mfma_f32_16x16x32_bf16 v[100:103], v[218:221], v[192:195], v[100:103]
	v_mfma_f32_16x16x32_bf16 v[96:99], v[226:229], v[192:195], v[96:99]
	v_mfma_f32_16x16x32_bf16 v[84:87], v[218:221], v[200:203], v[84:87]
	v_mfma_f32_16x16x32_bf16 v[80:83], v[226:229], v[200:203], v[80:83]
	v_mfma_f32_16x16x32_bf16 v[68:71], v[218:221], v[210:213], v[68:71]
	v_mfma_f32_16x16x32_bf16 v[64:67], v[226:229], v[210:213], v[64:67]
	s_setprio 0
	s_mov_b32 m0, s46
	v_lshl_add_u64 v[156:157], s[44:45], 0, v[128:129]
	s_barrier
	ds_read_b128 v[180:183], v159 offset:16384
	ds_read_b128 v[184:187], v159 offset:17408
	ds_read_b128 v[188:191], v159 offset:18432
	ds_read_b128 v[192:195], v159 offset:19456
	ds_read_b128 v[196:199], v159 offset:20480
	ds_read_b128 v[200:203], v159 offset:21504
	ds_read_b128 v[206:209], v159 offset:22528
	ds_read_b128 v[210:213], v159 offset:23552
	global_load_lds_dwordx4 v[156:157], off
	v_lshl_add_u64 v[160:161], s[44:45], 0, v[132:133]
	s_mov_b32 m0, s47
	s_nop 0
	global_load_lds_dwordx4 v[160:161], off
	s_barrier
	s_waitcnt lgkmcnt(0)
	s_setprio 1
	s_waitcnt lgkmcnt(0)
	v_mfma_f32_16x16x32_bf16 v[60:63], v[164:167], v[180:183], v[60:63]
	v_mfma_f32_16x16x32_bf16 v[56:59], v[172:175], v[180:183], v[56:59]
	v_mfma_f32_16x16x32_bf16 v[44:47], v[164:167], v[188:191], v[44:47]
	v_mfma_f32_16x16x32_bf16 v[40:43], v[172:175], v[188:191], v[40:43]
	v_mfma_f32_16x16x32_bf16 v[28:31], v[164:167], v[196:199], v[28:31]
	v_mfma_f32_16x16x32_bf16 v[24:27], v[172:175], v[196:199], v[24:27]
	v_mfma_f32_16x16x32_bf16 v[12:15], v[164:167], v[206:209], v[12:15]
	v_mfma_f32_16x16x32_bf16 v[8:11], v[172:175], v[206:209], v[8:11]
	v_mfma_f32_16x16x32_bf16 v[60:63], v[168:171], v[184:187], v[60:63]
	v_mfma_f32_16x16x32_bf16 v[56:59], v[176:179], v[184:187], v[56:59]
	v_mfma_f32_16x16x32_bf16 v[44:47], v[168:171], v[192:195], v[44:47]
	v_mfma_f32_16x16x32_bf16 v[40:43], v[176:179], v[192:195], v[40:43]
	v_mfma_f32_16x16x32_bf16 v[28:31], v[168:171], v[200:203], v[28:31]
	v_mfma_f32_16x16x32_bf16 v[24:27], v[176:179], v[200:203], v[24:27]
	v_mfma_f32_16x16x32_bf16 v[12:15], v[168:171], v[210:213], v[12:15]
	v_mfma_f32_16x16x32_bf16 v[8:11], v[176:179], v[210:213], v[8:11]
	s_setprio 0
	s_barrier
	s_add_u32 s68, s42, 0x40000
	s_addc_u32 s69, s43, 0
	s_add_i32 s67, s56, s33
	v_lshl_add_u64 v[164:165], s[68:69], 0, v[130:131]
	s_mov_b32 m0, s67
	s_nop 0
	global_load_lds_dwordx4 v[164:165], off
	v_lshl_add_u64 v[164:165], s[68:69], 0, v[134:135]
	s_add_i32 m0, s67, 0x2000
	s_nop 0
	global_load_lds_dwordx4 v[164:165], off
	s_waitcnt vmcnt(6)
	s_cmp_gt_u32 s66, 6
	s_cbranch_scc1 .Lds_P16_a_done
	s_cmp_eq_u32 s66, 6
	s_cbranch_scc1 .Lds_P16_a_pf
	s_cmp_eq_u32 s32, 0
	s_cbranch_scc1 .Lds_P16_a_done
	s_cmp_eq_u32 s66, 0
	s_cbranch_scc1 .Lds_P16_a_0
	s_cmp_eq_u32 s66, 2
	s_cbranch_scc1 .Lds_P16_a_1
	s_add_u32 s100, s98, 0x160000
	s_addc_u32 s101, s99, 0
	global_store_dwordx4 v239, v[248:251], s[100:101]
	s_branch .Lds_P16_a_done

.Lds_P16_a_pf:
	s_lshl_b32 s82, s8, 11
	s_add_u32 s100, s16, s82
	s_addc_u32 s101, s17, 0
	v_lshlrev_b32_e32 v252, 3, v145
	global_load_dwordx2 v[230:231], v252, s[100:101]
	global_load_dwordx2 v[232:233], v252, s[100:101] offset:128
	global_load_dwordx2 v[234:235], v252, s[100:101] offset:256
	global_load_dwordx2 v[236:237], v252, s[100:101] offset:384
	global_load_dwordx2 v[240:241], v252, s[100:101] offset:1024
	global_load_dwordx2 v[242:243], v252, s[100:101] offset:1152
	global_load_dwordx2 v[244:245], v252, s[100:101] offset:1280
	global_load_dwordx2 v[246:247], v252, s[100:101] offset:1408
.Lds_P16_a_done:
	s_barrier
	s_setprio 1
	v_mfma_f32_16x16x32_bf16 v[52:55], v[214:217], v[180:183], v[52:55]
	v_mfma_f32_16x16x32_bf16 v[48:51], v[222:225], v[180:183], v[48:51]
	v_mfma_f32_16x16x32_bf16 v[36:39], v[214:217], v[188:191], v[36:39]
	v_mfma_f32_16x16x32_bf16 v[32:35], v[222:225], v[188:191], v[32:35]
	v_mfma_f32_16x16x32_bf16 v[20:23], v[214:217], v[196:199], v[20:23]
	v_mfma_f32_16x16x32_bf16 v[16:19], v[222:225], v[196:199], v[16:19]
	v_mfma_f32_16x16x32_bf16 v[4:7], v[214:217], v[206:209], v[4:7]
	v_mfma_f32_16x16x32_bf16 v[0:3], v[222:225], v[206:209], v[0:3]
	v_mfma_f32_16x16x32_bf16 v[52:55], v[218:221], v[184:187], v[52:55]
	v_mfma_f32_16x16x32_bf16 v[48:51], v[226:229], v[184:187], v[48:51]
	v_mfma_f32_16x16x32_bf16 v[36:39], v[218:221], v[192:195], v[36:39]
	v_mfma_f32_16x16x32_bf16 v[32:35], v[226:229], v[192:195], v[32:35]
	v_mfma_f32_16x16x32_bf16 v[20:23], v[218:221], v[200:203], v[20:23]
	v_mfma_f32_16x16x32_bf16 v[16:19], v[226:229], v[200:203], v[16:19]
	v_mfma_f32_16x16x32_bf16 v[4:7], v[218:221], v[210:213], v[4:7]
	v_mfma_f32_16x16x32_bf16 v[0:3], v[226:229], v[210:213], v[0:3]
	s_setprio 0
	s_add_i32 s67, 0, 0x18000
	v_add_u32_e32 v144, s67, v149
	s_barrier
	ds_read_b128 v[164:167], v144
	ds_read_b128 v[168:171], v144 offset:1024
	ds_read_b128 v[172:175], v144 offset:2048
	ds_read_b128 v[176:179], v144 offset:3072
	s_add_u32 s44, s44, 0x40000
	s_addc_u32 s45, s45, 0
	s_mov_b32 m0, s48
	v_lshl_add_u64 v[214:215], s[44:45], 0, v[128:129]
	ds_read_b128 v[180:183], v159 offset:32768
	ds_read_b128 v[184:187], v159 offset:33792
	ds_read_b128 v[188:191], v159 offset:34816
	ds_read_b128 v[192:195], v159 offset:35840
	ds_read_b128 v[196:199], v159 offset:36864
	ds_read_b128 v[200:203], v159 offset:37888
	ds_read_b128 v[206:209], v159 offset:38912
	ds_read_b128 v[210:213], v159 offset:39936
	global_load_lds_dwordx4 v[214:215], off
	v_lshl_add_u64 v[214:215], s[44:45], 0, v[132:133]
	s_mov_b32 m0, s49
	s_nop 0
	global_load_lds_dwordx4 v[214:215], off
	s_waitcnt lgkmcnt(8)
	s_barrier
	s_waitcnt lgkmcnt(0)
	s_setprio 1
	s_waitcnt lgkmcnt(0)
	v_mfma_f32_16x16x32_bf16 v[124:127], v[164:167], v[180:183], v[124:127]
	v_mfma_f32_16x16x32_bf16 v[120:123], v[172:175], v[180:183], v[120:123]
	v_mfma_f32_16x16x32_bf16 v[108:111], v[164:167], v[188:191], v[108:111]
	v_mfma_f32_16x16x32_bf16 v[104:107], v[172:175], v[188:191], v[104:107]
	v_mfma_f32_16x16x32_bf16 v[92:95], v[164:167], v[196:199], v[92:95]
	v_mfma_f32_16x16x32_bf16 v[88:91], v[172:175], v[196:199], v[88:91]
	v_mfma_f32_16x16x32_bf16 v[76:79], v[164:167], v[206:209], v[76:79]
	v_mfma_f32_16x16x32_bf16 v[72:75], v[172:175], v[206:209], v[72:75]
	v_mfma_f32_16x16x32_bf16 v[124:127], v[168:171], v[184:187], v[124:127]
	v_mfma_f32_16x16x32_bf16 v[120:123], v[176:179], v[184:187], v[120:123]
	v_mfma_f32_16x16x32_bf16 v[108:111], v[168:171], v[192:195], v[108:111]
	v_mfma_f32_16x16x32_bf16 v[104:107], v[176:179], v[192:195], v[104:107]
	v_mfma_f32_16x16x32_bf16 v[92:95], v[168:171], v[200:203], v[92:95]
	v_mfma_f32_16x16x32_bf16 v[88:91], v[176:179], v[200:203], v[88:91]
	v_mfma_f32_16x16x32_bf16 v[76:79], v[168:171], v[210:213], v[76:79]
	v_mfma_f32_16x16x32_bf16 v[72:75], v[176:179], v[210:213], v[72:75]
	s_setprio 0
	s_barrier
	s_add_i32 s44, 0, 0x1c000
	s_add_i32 s45, s67, s33
	v_add_u32_e32 v144, s44, v149
	v_lshl_add_u64 v[146:147], v[146:147], 0, s[18:19]
	s_mov_b32 m0, s45
	ds_read_b128 v[214:217], v144
	ds_read_b128 v[218:221], v144 offset:1024
	ds_read_b128 v[222:225], v144 offset:2048
	ds_read_b128 v[226:229], v144 offset:3072
	global_load_lds_dwordx4 v[146:147], off
	v_lshl_add_u64 v[146:147], v[152:153], 0, s[18:19]
	s_add_i32 m0, s45, 0x2000
	s_nop 0
	global_load_lds_dwordx4 v[146:147], off
	s_barrier
	s_waitcnt lgkmcnt(0)
	s_setprio 1
	s_waitcnt lgkmcnt(0)
	v_mfma_f32_16x16x32_bf16 v[116:119], v[214:217], v[180:183], v[116:119]
	v_mfma_f32_16x16x32_bf16 v[112:115], v[222:225], v[180:183], v[112:115]
	v_mfma_f32_16x16x32_bf16 v[100:103], v[214:217], v[188:191], v[100:103]
	v_mfma_f32_16x16x32_bf16 v[96:99], v[222:225], v[188:191], v[96:99]
	v_mfma_f32_16x16x32_bf16 v[84:87], v[214:217], v[196:199], v[84:87]
	v_mfma_f32_16x16x32_bf16 v[80:83], v[222:225], v[196:199], v[80:83]
	v_mfma_f32_16x16x32_bf16 v[68:71], v[214:217], v[206:209], v[68:71]
	v_mfma_f32_16x16x32_bf16 v[64:67], v[222:225], v[206:209], v[64:67]
	v_mfma_f32_16x16x32_bf16 v[116:119], v[218:221], v[184:187], v[116:119]
	v_mfma_f32_16x16x32_bf16 v[112:115], v[226:229], v[184:187], v[112:115]
	v_mfma_f32_16x16x32_bf16 v[100:103], v[218:221], v[192:195], v[100:103]
	v_mfma_f32_16x16x32_bf16 v[96:99], v[226:229], v[192:195], v[96:99]
	v_mfma_f32_16x16x32_bf16 v[84:87], v[218:221], v[200:203], v[84:87]
	v_mfma_f32_16x16x32_bf16 v[80:83], v[226:229], v[200:203], v[80:83]
	v_mfma_f32_16x16x32_bf16 v[68:71], v[218:221], v[210:213], v[68:71]
	v_mfma_f32_16x16x32_bf16 v[64:67], v[226:229], v[210:213], v[64:67]
	s_setprio 0
	s_mov_b32 m0, s51
	v_lshl_add_u64 v[146:147], v[156:157], 0, s[18:19]
	s_barrier
	ds_read_b128 v[180:183], v159 offset:49152
	ds_read_b128 v[184:187], v159 offset:50176
	ds_read_b128 v[188:191], v159 offset:51200
	ds_read_b128 v[192:195], v159 offset:52224
	ds_read_b128 v[196:199], v159 offset:53248
	ds_read_b128 v[200:203], v159 offset:54272
	ds_read_b128 v[206:209], v159 offset:55296
	ds_read_b128 v[210:213], v159 offset:56320
	global_load_lds_dwordx4 v[146:147], off
	v_lshl_add_u64 v[146:147], v[160:161], 0, s[18:19]
	s_mov_b32 m0, s52
	s_nop 0
	global_load_lds_dwordx4 v[146:147], off
	s_barrier
	s_waitcnt lgkmcnt(0)
	s_setprio 1
	s_waitcnt lgkmcnt(0)
	v_mfma_f32_16x16x32_bf16 v[60:63], v[164:167], v[180:183], v[60:63]
	v_mfma_f32_16x16x32_bf16 v[56:59], v[172:175], v[180:183], v[56:59]
	v_mfma_f32_16x16x32_bf16 v[44:47], v[164:167], v[188:191], v[44:47]
	v_mfma_f32_16x16x32_bf16 v[40:43], v[172:175], v[188:191], v[40:43]
	v_mfma_f32_16x16x32_bf16 v[28:31], v[164:167], v[196:199], v[28:31]
	v_mfma_f32_16x16x32_bf16 v[24:27], v[172:175], v[196:199], v[24:27]
	v_mfma_f32_16x16x32_bf16 v[12:15], v[164:167], v[206:209], v[12:15]
	v_mfma_f32_16x16x32_bf16 v[8:11], v[172:175], v[206:209], v[8:11]
	v_mfma_f32_16x16x32_bf16 v[60:63], v[168:171], v[184:187], v[60:63]
	v_mfma_f32_16x16x32_bf16 v[56:59], v[176:179], v[184:187], v[56:59]
	v_mfma_f32_16x16x32_bf16 v[44:47], v[168:171], v[192:195], v[44:47]
	v_mfma_f32_16x16x32_bf16 v[40:43], v[176:179], v[192:195], v[40:43]
	v_mfma_f32_16x16x32_bf16 v[28:31], v[168:171], v[200:203], v[28:31]
	v_mfma_f32_16x16x32_bf16 v[24:27], v[176:179], v[200:203], v[24:27]
	v_mfma_f32_16x16x32_bf16 v[12:15], v[168:171], v[210:213], v[12:15]
	v_mfma_f32_16x16x32_bf16 v[8:11], v[176:179], v[210:213], v[8:11]
	s_setprio 0
	s_barrier
	s_add_u32 s42, s42, 0x40080
	s_addc_u32 s43, s43, 0
	s_add_i32 s44, s44, s33
	v_lshl_add_u64 v[146:147], s[42:43], 0, v[130:131]
	s_mov_b32 m0, s44
	s_nop 0
	global_load_lds_dwordx4 v[146:147], off
	v_lshl_add_u64 v[146:147], s[42:43], 0, v[134:135]
	s_add_i32 m0, s44, 0x2000
	s_nop 0
	global_load_lds_dwordx4 v[146:147], off
	s_waitcnt vmcnt(6)
	s_cmp_gt_u32 s66, 4
	s_cbranch_scc1 .Lds_P16_b_done
	s_cmp_eq_u32 s32, 0
	s_cbranch_scc1 .Lds_P16_b_done
	s_cmp_eq_u32 s66, 0
	s_cbranch_scc1 .Lds_P16_b_0
	s_cmp_eq_u32 s66, 2
	s_cbranch_scc1 .Lds_P16_b_1
	s_add_u32 s100, s98, 0x160000
	s_addc_u32 s101, s99, 0
	global_store_dwordx4 v239, v[252:255], s[100:101] offset:256
	s_branch .Lds_P16_b_done

.Lds_P16_b_done:
	s_barrier
	s_setprio 1
	v_mfma_f32_16x16x32_bf16 v[52:55], v[214:217], v[180:183], v[52:55]
	v_mfma_f32_16x16x32_bf16 v[48:51], v[222:225], v[180:183], v[48:51]
	v_mfma_f32_16x16x32_bf16 v[36:39], v[214:217], v[188:191], v[36:39]
	v_mfma_f32_16x16x32_bf16 v[32:35], v[222:225], v[188:191], v[32:35]
	v_mfma_f32_16x16x32_bf16 v[20:23], v[214:217], v[196:199], v[20:23]
	v_mfma_f32_16x16x32_bf16 v[16:19], v[222:225], v[196:199], v[16:19]
	v_mfma_f32_16x16x32_bf16 v[4:7], v[214:217], v[206:209], v[4:7]
	v_mfma_f32_16x16x32_bf16 v[0:3], v[222:225], v[206:209], v[0:3]
	v_mfma_f32_16x16x32_bf16 v[52:55], v[218:221], v[184:187], v[52:55]
	v_mfma_f32_16x16x32_bf16 v[48:51], v[226:229], v[184:187], v[48:51]
	v_mfma_f32_16x16x32_bf16 v[36:39], v[218:221], v[192:195], v[36:39]
	v_mfma_f32_16x16x32_bf16 v[32:35], v[226:229], v[192:195], v[32:35]
	v_mfma_f32_16x16x32_bf16 v[20:23], v[218:221], v[200:203], v[20:23]
	v_mfma_f32_16x16x32_bf16 v[16:19], v[226:229], v[200:203], v[16:19]
	v_mfma_f32_16x16x32_bf16 v[4:7], v[218:221], v[210:213], v[4:7]
	v_mfma_f32_16x16x32_bf16 v[0:3], v[226:229], v[210:213], v[0:3]
	s_setprio 0
	s_add_i32 s66, s66, 2
	s_add_u32 s10, s10, 0x100
	s_addc_u32 s11, s11, 0
	s_add_u32 s64, s64, 0x100
	s_addc_u32 s65, s65, 0
	s_cmp_gt_u32 s66, 13
	s_barrier
	s_cbranch_scc0 .LBB0_1981
.Lepi_P16_start:
	s_mul_i32 s82, s8, 0x200000
	s_lshl_b32 s84, s62, 9
	s_add_u32 s82, s82, s84
	s_add_u32 s84, s14, s82
	s_addc_u32 s85, s15, 0
	v_mov_b32_e32 v144, 0x358637bd
	v_ffbh_u32_e32 v172, v231
	v_ffbh_u32_e32 v173, v233
	v_ffbh_u32_e32 v174, v235
	v_ffbh_u32_e32 v175, v237
	v_ffbh_u32_e32 v176, v241
	v_ffbh_u32_e32 v177, v243
	v_ffbh_u32_e32 v178, v245
	v_ffbh_u32_e32 v179, v247
	v_min_u32_e32 v172, 32, v172
	v_min_u32_e32 v173, 32, v173
	v_min_u32_e32 v174, 32, v174
	v_min_u32_e32 v175, 32, v175
	v_min_u32_e32 v176, 32, v176
	v_min_u32_e32 v177, 32, v177
	v_min_u32_e32 v178, 32, v178
	v_min_u32_e32 v179, 32, v179
	v_lshlrev_b64 v[230:231], v172, v[230:231]
	v_lshlrev_b64 v[232:233], v173, v[232:233]
	v_lshlrev_b64 v[234:235], v174, v[234:235]
	v_lshlrev_b64 v[236:237], v175, v[236:237]
	v_lshlrev_b64 v[240:241], v176, v[240:241]
	v_lshlrev_b64 v[242:243], v177, v[242:243]
	v_lshlrev_b64 v[244:245], v178, v[244:245]
	v_lshlrev_b64 v[246:247], v179, v[246:247]
	v_min_u32_e32 v230, 1, v230
	v_min_u32_e32 v232, 1, v232
	v_min_u32_e32 v234, 1, v234
	v_min_u32_e32 v236, 1, v236
	v_min_u32_e32 v240, 1, v240
	v_min_u32_e32 v242, 1, v242
	v_min_u32_e32 v244, 1, v244
	v_min_u32_e32 v246, 1, v246
	v_or_b32_e32 v231, v231, v230
	v_or_b32_e32 v233, v233, v232
	v_or_b32_e32 v235, v235, v234
	v_or_b32_e32 v237, v237, v236
	v_or_b32_e32 v241, v241, v240
	v_or_b32_e32 v243, v243, v242
	v_or_b32_e32 v245, v245, v244
	v_or_b32_e32 v247, v247, v246
	v_cvt_f32_u32_e32 v231, v231
	v_cvt_f32_u32_e32 v233, v233
	v_cvt_f32_u32_e32 v235, v235
	v_cvt_f32_u32_e32 v237, v237
	v_cvt_f32_u32_e32 v241, v241
	v_cvt_f32_u32_e32 v243, v243
	v_cvt_f32_u32_e32 v245, v245
	v_cvt_f32_u32_e32 v247, v247
	v_sub_u32_e32 v172, 32, v172
	v_sub_u32_e32 v173, 32, v173
	v_sub_u32_e32 v174, 32, v174
	v_sub_u32_e32 v175, 32, v175
	v_sub_u32_e32 v176, 32, v176
	v_sub_u32_e32 v177, 32, v177
	v_sub_u32_e32 v178, 32, v178
	v_sub_u32_e32 v179, 32, v179
	v_ldexp_f32 v231, v231, v172
	v_ldexp_f32 v233, v233, v173
	v_ldexp_f32 v235, v235, v174
	v_ldexp_f32 v237, v237, v175
	v_ldexp_f32 v241, v241, v176
	v_ldexp_f32 v243, v243, v177
	v_ldexp_f32 v245, v245, v178
	v_ldexp_f32 v247, v247, v179
	v_fmamk_f32 v231, v231, 0x2e800000, v144
	v_fmamk_f32 v233, v233, 0x2e800000, v144
	v_fmamk_f32 v235, v235, 0x2e800000, v144
	v_fmamk_f32 v237, v237, 0x2e800000, v144
	v_fmamk_f32 v241, v241, 0x2e800000, v144
	v_fmamk_f32 v243, v243, 0x2e800000, v144
	v_fmamk_f32 v245, v245, 0x2e800000, v144
	v_fmamk_f32 v247, v247, 0x2e800000, v144
	v_rsq_f32_e32 v164, v231
	v_rsq_f32_e32 v165, v233
	v_rsq_f32_e32 v166, v235
	v_rsq_f32_e32 v167, v237
	v_rsq_f32_e32 v168, v241
	v_rsq_f32_e32 v169, v243
	v_rsq_f32_e32 v170, v245
	v_rsq_f32_e32 v171, v247
	s_nop 0
	v_pk_mul_f32 v[124:125], v[124:125], v[164:165] op_sel_hi:[1,0]
	v_pk_mul_f32 v[126:127], v[126:127], v[164:165] op_sel_hi:[1,0]
	v_pk_mul_f32 v[120:121], v[120:121], v[164:165] op_sel_hi:[1,0]
	v_pk_mul_f32 v[122:123], v[122:123], v[164:165] op_sel_hi:[1,0]
	v_max_f32_e32 v124, 0, v124
	v_max_f32_e32 v125, 0, v125
	v_max_f32_e32 v126, 0, v126
	v_max_f32_e32 v127, 0, v127
	v_max_f32_e32 v120, 0, v120
	v_max_f32_e32 v121, 0, v121
	v_max_f32_e32 v122, 0, v122
	v_max_f32_e32 v123, 0, v123
	v_pk_mul_f32 v[124:125], v[124:125], v[124:125]
	v_pk_mul_f32 v[126:127], v[126:127], v[126:127]
	v_pk_mul_f32 v[120:121], v[120:121], v[120:121]
	v_pk_mul_f32 v[122:123], v[122:123], v[122:123]
	v_cvt_pk_bf16_f32 v124, v124, v125
	v_cvt_pk_bf16_f32 v125, v126, v127
	v_cvt_pk_bf16_f32 v126, v120, v121
	v_cvt_pk_bf16_f32 v127, v122, v123
	global_store_dwordx4 v239, v[124:127], s[84:85]
	v_pk_mul_f32 v[116:117], v[116:117], v[164:165] op_sel_hi:[1,0]
	v_pk_mul_f32 v[118:119], v[118:119], v[164:165] op_sel_hi:[1,0]
	v_pk_mul_f32 v[112:113], v[112:113], v[164:165] op_sel_hi:[1,0]
	v_pk_mul_f32 v[114:115], v[114:115], v[164:165] op_sel_hi:[1,0]
	v_max_f32_e32 v116, 0, v116
	v_max_f32_e32 v117, 0, v117
	v_max_f32_e32 v118, 0, v118
	v_max_f32_e32 v119, 0, v119
	v_max_f32_e32 v112, 0, v112
	v_max_f32_e32 v113, 0, v113
	v_max_f32_e32 v114, 0, v114
	v_max_f32_e32 v115, 0, v115
	v_pk_mul_f32 v[116:117], v[116:117], v[116:117]
	v_pk_mul_f32 v[118:119], v[118:119], v[118:119]
	v_pk_mul_f32 v[112:113], v[112:113], v[112:113]
	v_pk_mul_f32 v[114:115], v[114:115], v[114:115]
	v_cvt_pk_bf16_f32 v116, v116, v117
	v_cvt_pk_bf16_f32 v117, v118, v119
	v_cvt_pk_bf16_f32 v118, v112, v113
	v_cvt_pk_bf16_f32 v119, v114, v115
	global_store_dwordx4 v239, v[116:119], s[84:85] offset:256
	v_pk_mul_f32 v[108:109], v[108:109], v[164:165] op_sel:[0,1] op_sel_hi:[1,1]
	v_pk_mul_f32 v[110:111], v[110:111], v[164:165] op_sel:[0,1] op_sel_hi:[1,1]
	v_pk_mul_f32 v[104:105], v[104:105], v[164:165] op_sel:[0,1] op_sel_hi:[1,1]
	v_pk_mul_f32 v[106:107], v[106:107], v[164:165] op_sel:[0,1] op_sel_hi:[1,1]
	v_max_f32_e32 v108, 0, v108
	v_max_f32_e32 v109, 0, v109
	v_max_f32_e32 v110, 0, v110
	v_max_f32_e32 v111, 0, v111
	v_max_f32_e32 v104, 0, v104
	v_max_f32_e32 v105, 0, v105
	v_max_f32_e32 v106, 0, v106
	v_max_f32_e32 v107, 0, v107
	v_pk_mul_f32 v[108:109], v[108:109], v[108:109]
	v_pk_mul_f32 v[110:111], v[110:111], v[110:111]
	v_pk_mul_f32 v[104:105], v[104:105], v[104:105]
	v_pk_mul_f32 v[106:107], v[106:107], v[106:107]
	v_cvt_pk_bf16_f32 v108, v108, v109
	v_cvt_pk_bf16_f32 v109, v110, v111
	v_cvt_pk_bf16_f32 v110, v104, v105
	v_cvt_pk_bf16_f32 v111, v106, v107
	s_add_u32 s100, s84, 0x20000
	s_addc_u32 s101, s85, 0
	global_store_dwordx4 v239, v[108:111], s[100:101]
	v_pk_mul_f32 v[100:101], v[100:101], v[164:165] op_sel:[0,1] op_sel_hi:[1,1]
	v_pk_mul_f32 v[102:103], v[102:103], v[164:165] op_sel:[0,1] op_sel_hi:[1,1]
	v_pk_mul_f32 v[96:97], v[96:97], v[164:165] op_sel:[0,1] op_sel_hi:[1,1]
	v_pk_mul_f32 v[98:99], v[98:99], v[164:165] op_sel:[0,1] op_sel_hi:[1,1]
	v_max_f32_e32 v100, 0, v100
	v_max_f32_e32 v101, 0, v101
	v_max_f32_e32 v102, 0, v102
	v_max_f32_e32 v103, 0, v103
	v_max_f32_e32 v96, 0, v96
	v_max_f32_e32 v97, 0, v97
	v_max_f32_e32 v98, 0, v98
	v_max_f32_e32 v99, 0, v99
	v_pk_mul_f32 v[100:101], v[100:101], v[100:101]
	v_pk_mul_f32 v[102:103], v[102:103], v[102:103]
	v_pk_mul_f32 v[96:97], v[96:97], v[96:97]
	v_pk_mul_f32 v[98:99], v[98:99], v[98:99]
	v_cvt_pk_bf16_f32 v100, v100, v101
	v_cvt_pk_bf16_f32 v101, v102, v103
	v_cvt_pk_bf16_f32 v102, v96, v97
	v_cvt_pk_bf16_f32 v103, v98, v99
	s_add_u32 s100, s84, 0x20000
	s_addc_u32 s101, s85, 0
	global_store_dwordx4 v239, v[100:103], s[100:101] offset:256
	v_pk_mul_f32 v[92:93], v[92:93], v[166:167] op_sel_hi:[1,0]
	v_pk_mul_f32 v[94:95], v[94:95], v[166:167] op_sel_hi:[1,0]
	v_pk_mul_f32 v[88:89], v[88:89], v[166:167] op_sel_hi:[1,0]
	v_pk_mul_f32 v[90:91], v[90:91], v[166:167] op_sel_hi:[1,0]
	v_max_f32_e32 v92, 0, v92
	v_max_f32_e32 v93, 0, v93
	v_max_f32_e32 v94, 0, v94
	v_max_f32_e32 v95, 0, v95
	v_max_f32_e32 v88, 0, v88
	v_max_f32_e32 v89, 0, v89
	v_max_f32_e32 v90, 0, v90
	v_max_f32_e32 v91, 0, v91
	v_pk_mul_f32 v[92:93], v[92:93], v[92:93]
	v_pk_mul_f32 v[94:95], v[94:95], v[94:95]
	v_pk_mul_f32 v[88:89], v[88:89], v[88:89]
	v_pk_mul_f32 v[90:91], v[90:91], v[90:91]
	v_cvt_pk_bf16_f32 v92, v92, v93
	v_cvt_pk_bf16_f32 v93, v94, v95
	v_cvt_pk_bf16_f32 v94, v88, v89
	v_cvt_pk_bf16_f32 v95, v90, v91
	s_add_u32 s100, s84, 0x40000
	s_addc_u32 s101, s85, 0
	global_store_dwordx4 v239, v[92:95], s[100:101]
	v_pk_mul_f32 v[84:85], v[84:85], v[166:167] op_sel_hi:[1,0]
	v_pk_mul_f32 v[86:87], v[86:87], v[166:167] op_sel_hi:[1,0]
	v_pk_mul_f32 v[80:81], v[80:81], v[166:167] op_sel_hi:[1,0]
	v_pk_mul_f32 v[82:83], v[82:83], v[166:167] op_sel_hi:[1,0]
	v_max_f32_e32 v84, 0, v84
	v_max_f32_e32 v85, 0, v85
	v_max_f32_e32 v86, 0, v86
	v_max_f32_e32 v87, 0, v87
	v_max_f32_e32 v80, 0, v80
	v_max_f32_e32 v81, 0, v81
	v_max_f32_e32 v82, 0, v82
	v_max_f32_e32 v83, 0, v83
	v_pk_mul_f32 v[84:85], v[84:85], v[84:85]
	v_pk_mul_f32 v[86:87], v[86:87], v[86:87]
	v_pk_mul_f32 v[80:81], v[80:81], v[80:81]
	v_pk_mul_f32 v[82:83], v[82:83], v[82:83]
	v_cvt_pk_bf16_f32 v84, v84, v85
	v_cvt_pk_bf16_f32 v85, v86, v87
	v_cvt_pk_bf16_f32 v86, v80, v81
	v_cvt_pk_bf16_f32 v87, v82, v83
	s_add_u32 s100, s84, 0x40000
	s_addc_u32 s101, s85, 0
	global_store_dwordx4 v239, v[84:87], s[100:101] offset:256
	v_pk_mul_f32 v[76:77], v[76:77], v[166:167] op_sel:[0,1] op_sel_hi:[1,1]
	v_pk_mul_f32 v[78:79], v[78:79], v[166:167] op_sel:[0,1] op_sel_hi:[1,1]
	v_pk_mul_f32 v[72:73], v[72:73], v[166:167] op_sel:[0,1] op_sel_hi:[1,1]
	v_pk_mul_f32 v[74:75], v[74:75], v[166:167] op_sel:[0,1] op_sel_hi:[1,1]
	v_max_f32_e32 v76, 0, v76
	v_max_f32_e32 v77, 0, v77
	v_max_f32_e32 v78, 0, v78
	v_max_f32_e32 v79, 0, v79
	v_max_f32_e32 v72, 0, v72
	v_max_f32_e32 v73, 0, v73
	v_max_f32_e32 v74, 0, v74
	v_max_f32_e32 v75, 0, v75
	v_pk_mul_f32 v[76:77], v[76:77], v[76:77]
	v_pk_mul_f32 v[78:79], v[78:79], v[78:79]
	v_pk_mul_f32 v[72:73], v[72:73], v[72:73]
	v_pk_mul_f32 v[74:75], v[74:75], v[74:75]
	v_cvt_pk_bf16_f32 v76, v76, v77
	v_cvt_pk_bf16_f32 v77, v78, v79
	v_cvt_pk_bf16_f32 v78, v72, v73
	v_cvt_pk_bf16_f32 v79, v74, v75
	s_add_u32 s100, s84, 0x60000
	s_addc_u32 s101, s85, 0
	global_store_dwordx4 v239, v[76:79], s[100:101]
	v_pk_mul_f32 v[68:69], v[68:69], v[166:167] op_sel:[0,1] op_sel_hi:[1,1]
	v_pk_mul_f32 v[70:71], v[70:71], v[166:167] op_sel:[0,1] op_sel_hi:[1,1]
	v_pk_mul_f32 v[64:65], v[64:65], v[166:167] op_sel:[0,1] op_sel_hi:[1,1]
	v_pk_mul_f32 v[66:67], v[66:67], v[166:167] op_sel:[0,1] op_sel_hi:[1,1]
	v_max_f32_e32 v68, 0, v68
	v_max_f32_e32 v69, 0, v69
	v_max_f32_e32 v70, 0, v70
	v_max_f32_e32 v71, 0, v71
	v_max_f32_e32 v64, 0, v64
	v_max_f32_e32 v65, 0, v65
	v_max_f32_e32 v66, 0, v66
	v_max_f32_e32 v67, 0, v67
	v_pk_mul_f32 v[68:69], v[68:69], v[68:69]
	v_pk_mul_f32 v[70:71], v[70:71], v[70:71]
	v_pk_mul_f32 v[64:65], v[64:65], v[64:65]
	v_pk_mul_f32 v[66:67], v[66:67], v[66:67]
	v_cvt_pk_bf16_f32 v68, v68, v69
	v_cvt_pk_bf16_f32 v69, v70, v71
	v_cvt_pk_bf16_f32 v70, v64, v65
	v_cvt_pk_bf16_f32 v71, v66, v67
	s_add_u32 s100, s84, 0x60000
	s_addc_u32 s101, s85, 0
	global_store_dwordx4 v239, v[68:71], s[100:101] offset:256
	v_pk_mul_f32 v[60:61], v[60:61], v[168:169] op_sel_hi:[1,0]
	v_pk_mul_f32 v[62:63], v[62:63], v[168:169] op_sel_hi:[1,0]
	v_pk_mul_f32 v[56:57], v[56:57], v[168:169] op_sel_hi:[1,0]
	v_pk_mul_f32 v[58:59], v[58:59], v[168:169] op_sel_hi:[1,0]
	v_max_f32_e32 v60, 0, v60
	v_max_f32_e32 v61, 0, v61
	v_max_f32_e32 v62, 0, v62
	v_max_f32_e32 v63, 0, v63
	v_max_f32_e32 v56, 0, v56
	v_max_f32_e32 v57, 0, v57
	v_max_f32_e32 v58, 0, v58
	v_max_f32_e32 v59, 0, v59
	v_pk_mul_f32 v[60:61], v[60:61], v[60:61]
	v_pk_mul_f32 v[62:63], v[62:63], v[62:63]
	v_pk_mul_f32 v[56:57], v[56:57], v[56:57]
	v_pk_mul_f32 v[58:59], v[58:59], v[58:59]
	v_cvt_pk_bf16_f32 v60, v60, v61
	v_cvt_pk_bf16_f32 v61, v62, v63
	v_cvt_pk_bf16_f32 v62, v56, v57
	v_cvt_pk_bf16_f32 v63, v58, v59
	s_add_u32 s100, s84, 0x100000
	s_addc_u32 s101, s85, 0
	global_store_dwordx4 v239, v[60:63], s[100:101]
	v_pk_mul_f32 v[52:53], v[52:53], v[168:169] op_sel_hi:[1,0]
	v_pk_mul_f32 v[54:55], v[54:55], v[168:169] op_sel_hi:[1,0]
	v_pk_mul_f32 v[48:49], v[48:49], v[168:169] op_sel_hi:[1,0]
	v_pk_mul_f32 v[50:51], v[50:51], v[168:169] op_sel_hi:[1,0]
	v_max_f32_e32 v52, 0, v52
	v_max_f32_e32 v53, 0, v53
	v_max_f32_e32 v54, 0, v54
	v_max_f32_e32 v55, 0, v55
	v_max_f32_e32 v48, 0, v48
	v_max_f32_e32 v49, 0, v49
	v_max_f32_e32 v50, 0, v50
	v_max_f32_e32 v51, 0, v51
	v_pk_mul_f32 v[52:53], v[52:53], v[52:53]
	v_pk_mul_f32 v[54:55], v[54:55], v[54:55]
	v_pk_mul_f32 v[48:49], v[48:49], v[48:49]
	v_pk_mul_f32 v[50:51], v[50:51], v[50:51]
	v_cvt_pk_bf16_f32 v52, v52, v53
	v_cvt_pk_bf16_f32 v53, v54, v55
	v_cvt_pk_bf16_f32 v54, v48, v49
	v_cvt_pk_bf16_f32 v55, v50, v51
	s_add_u32 s100, s84, 0x100000
	s_addc_u32 s101, s85, 0
	global_store_dwordx4 v239, v[52:55], s[100:101] offset:256
	v_pk_mul_f32 v[44:45], v[44:45], v[168:169] op_sel:[0,1] op_sel_hi:[1,1]
	v_pk_mul_f32 v[46:47], v[46:47], v[168:169] op_sel:[0,1] op_sel_hi:[1,1]
	v_pk_mul_f32 v[40:41], v[40:41], v[168:169] op_sel:[0,1] op_sel_hi:[1,1]
	v_pk_mul_f32 v[42:43], v[42:43], v[168:169] op_sel:[0,1] op_sel_hi:[1,1]
	v_max_f32_e32 v44, 0, v44
	v_max_f32_e32 v45, 0, v45
	v_max_f32_e32 v46, 0, v46
	v_max_f32_e32 v47, 0, v47
	v_max_f32_e32 v40, 0, v40
	v_max_f32_e32 v41, 0, v41
	v_max_f32_e32 v42, 0, v42
	v_max_f32_e32 v43, 0, v43
	v_pk_mul_f32 v[44:45], v[44:45], v[44:45]
	v_pk_mul_f32 v[46:47], v[46:47], v[46:47]
	v_pk_mul_f32 v[40:41], v[40:41], v[40:41]
	v_pk_mul_f32 v[42:43], v[42:43], v[42:43]
	v_cvt_pk_bf16_f32 v230, v44, v45
	v_cvt_pk_bf16_f32 v231, v46, v47
	v_cvt_pk_bf16_f32 v232, v40, v41
	v_cvt_pk_bf16_f32 v233, v42, v43
	v_pk_mul_f32 v[36:37], v[36:37], v[168:169] op_sel:[0,1] op_sel_hi:[1,1]
	v_pk_mul_f32 v[38:39], v[38:39], v[168:169] op_sel:[0,1] op_sel_hi:[1,1]
	v_pk_mul_f32 v[32:33], v[32:33], v[168:169] op_sel:[0,1] op_sel_hi:[1,1]
	v_pk_mul_f32 v[34:35], v[34:35], v[168:169] op_sel:[0,1] op_sel_hi:[1,1]
	v_max_f32_e32 v36, 0, v36
	v_max_f32_e32 v37, 0, v37
	v_max_f32_e32 v38, 0, v38
	v_max_f32_e32 v39, 0, v39
	v_max_f32_e32 v32, 0, v32
	v_max_f32_e32 v33, 0, v33
	v_max_f32_e32 v34, 0, v34
	v_max_f32_e32 v35, 0, v35
	v_pk_mul_f32 v[36:37], v[36:37], v[36:37]
	v_pk_mul_f32 v[38:39], v[38:39], v[38:39]
	v_pk_mul_f32 v[32:33], v[32:33], v[32:33]
	v_pk_mul_f32 v[34:35], v[34:35], v[34:35]
	v_cvt_pk_bf16_f32 v234, v36, v37
	v_cvt_pk_bf16_f32 v235, v38, v39
	v_cvt_pk_bf16_f32 v236, v32, v33
	v_cvt_pk_bf16_f32 v237, v34, v35
	v_pk_mul_f32 v[28:29], v[28:29], v[170:171] op_sel_hi:[1,0]
	v_pk_mul_f32 v[30:31], v[30:31], v[170:171] op_sel_hi:[1,0]
	v_pk_mul_f32 v[24:25], v[24:25], v[170:171] op_sel_hi:[1,0]
	v_pk_mul_f32 v[26:27], v[26:27], v[170:171] op_sel_hi:[1,0]
	v_max_f32_e32 v28, 0, v28
	v_max_f32_e32 v29, 0, v29
	v_max_f32_e32 v30, 0, v30
	v_max_f32_e32 v31, 0, v31
	v_max_f32_e32 v24, 0, v24
	v_max_f32_e32 v25, 0, v25
	v_max_f32_e32 v26, 0, v26
	v_max_f32_e32 v27, 0, v27
	v_pk_mul_f32 v[28:29], v[28:29], v[28:29]
	v_pk_mul_f32 v[30:31], v[30:31], v[30:31]
	v_pk_mul_f32 v[24:25], v[24:25], v[24:25]
	v_pk_mul_f32 v[26:27], v[26:27], v[26:27]
	v_cvt_pk_bf16_f32 v240, v28, v29
	v_cvt_pk_bf16_f32 v241, v30, v31
	v_cvt_pk_bf16_f32 v242, v24, v25
	v_cvt_pk_bf16_f32 v243, v26, v27
	v_pk_mul_f32 v[20:21], v[20:21], v[170:171] op_sel_hi:[1,0]
	v_pk_mul_f32 v[22:23], v[22:23], v[170:171] op_sel_hi:[1,0]
	v_pk_mul_f32 v[16:17], v[16:17], v[170:171] op_sel_hi:[1,0]
	v_pk_mul_f32 v[18:19], v[18:19], v[170:171] op_sel_hi:[1,0]
	v_max_f32_e32 v20, 0, v20
	v_max_f32_e32 v21, 0, v21
	v_max_f32_e32 v22, 0, v22
	v_max_f32_e32 v23, 0, v23
	v_max_f32_e32 v16, 0, v16
	v_max_f32_e32 v17, 0, v17
	v_max_f32_e32 v18, 0, v18
	v_max_f32_e32 v19, 0, v19
	v_pk_mul_f32 v[20:21], v[20:21], v[20:21]
	v_pk_mul_f32 v[22:23], v[22:23], v[22:23]
	v_pk_mul_f32 v[16:17], v[16:17], v[16:17]
	v_pk_mul_f32 v[18:19], v[18:19], v[18:19]
	v_cvt_pk_bf16_f32 v244, v20, v21
	v_cvt_pk_bf16_f32 v245, v22, v23
	v_cvt_pk_bf16_f32 v246, v16, v17
	v_cvt_pk_bf16_f32 v247, v18, v19
	v_pk_mul_f32 v[12:13], v[12:13], v[170:171] op_sel:[0,1] op_sel_hi:[1,1]
	v_pk_mul_f32 v[14:15], v[14:15], v[170:171] op_sel:[0,1] op_sel_hi:[1,1]
	v_pk_mul_f32 v[8:9], v[8:9], v[170:171] op_sel:[0,1] op_sel_hi:[1,1]
	v_pk_mul_f32 v[10:11], v[10:11], v[170:171] op_sel:[0,1] op_sel_hi:[1,1]
	v_max_f32_e32 v12, 0, v12
	v_max_f32_e32 v13, 0, v13
	v_max_f32_e32 v14, 0, v14
	v_max_f32_e32 v15, 0, v15
	v_max_f32_e32 v8, 0, v8
	v_max_f32_e32 v9, 0, v9
	v_max_f32_e32 v10, 0, v10
	v_max_f32_e32 v11, 0, v11
	v_pk_mul_f32 v[12:13], v[12:13], v[12:13]
	v_pk_mul_f32 v[14:15], v[14:15], v[14:15]
	v_pk_mul_f32 v[8:9], v[8:9], v[8:9]
	v_pk_mul_f32 v[10:11], v[10:11], v[10:11]
	v_cvt_pk_bf16_f32 v248, v12, v13
	v_cvt_pk_bf16_f32 v249, v14, v15
	v_cvt_pk_bf16_f32 v250, v8, v9
	v_cvt_pk_bf16_f32 v251, v10, v11
	v_pk_mul_f32 v[4:5], v[4:5], v[170:171] op_sel:[0,1] op_sel_hi:[1,1]
	v_pk_mul_f32 v[6:7], v[6:7], v[170:171] op_sel:[0,1] op_sel_hi:[1,1]
	v_pk_mul_f32 v[0:1], v[0:1], v[170:171] op_sel:[0,1] op_sel_hi:[1,1]
	v_pk_mul_f32 v[2:3], v[2:3], v[170:171] op_sel:[0,1] op_sel_hi:[1,1]
	v_max_f32_e32 v4, 0, v4
	v_max_f32_e32 v5, 0, v5
	v_max_f32_e32 v6, 0, v6
	v_max_f32_e32 v7, 0, v7
	v_max_f32_e32 v0, 0, v0
	v_max_f32_e32 v1, 0, v1
	v_max_f32_e32 v2, 0, v2
	v_max_f32_e32 v3, 0, v3
	v_pk_mul_f32 v[4:5], v[4:5], v[4:5]
	v_pk_mul_f32 v[6:7], v[6:7], v[6:7]
	v_pk_mul_f32 v[0:1], v[0:1], v[0:1]
	v_pk_mul_f32 v[2:3], v[2:3], v[2:3]
	v_cvt_pk_bf16_f32 v252, v4, v5
	v_cvt_pk_bf16_f32 v253, v6, v7
	v_cvt_pk_bf16_f32 v254, v0, v1
	v_cvt_pk_bf16_f32 v255, v2, v3
	s_mov_b64 s[42:43], s[40:41]
	s_and_b64 vcc, exec, s[6:7]
	s_mov_b32 s62, s34
	s_mov_b32 s8, s36
	s_mov_b64 s[10:11], s[38:39]
	s_mov_b64 s[98:99], s[84:85]
	s_mov_b32 s32, 1
	s_cbranch_vccz .LBB0_1974
	s_add_u32 s100, s84, 0x120000
	s_addc_u32 s101, s85, 0
	global_store_dwordx4 v239, v[230:233], s[100:101]
	s_add_u32 s100, s84, 0x120000
	s_addc_u32 s101, s85, 0
	global_store_dwordx4 v239, v[234:237], s[100:101] offset:256
	s_add_u32 s100, s84, 0x140000
	s_addc_u32 s101, s85, 0
	global_store_dwordx4 v239, v[240:243], s[100:101]
	s_add_u32 s100, s84, 0x140000
	s_addc_u32 s101, s85, 0
	global_store_dwordx4 v239, v[244:247], s[100:101] offset:256
	s_add_u32 s100, s84, 0x160000
	s_addc_u32 s101, s85, 0
	global_store_dwordx4 v239, v[248:251], s[100:101]
	s_add_u32 s100, s84, 0x160000
	s_addc_u32 s101, s85, 0
	global_store_dwordx4 v239, v[252:255], s[100:101] offset:256
	s_waitcnt vmcnt(0)
	s_cmpk_gt_u32 s0, 0xff
	s_cbranch_scc1 .LBB0_1985
	s_barrier
